# v6 + thin-phase gain loads hoisted out of the row loop (T1,T3) + prologue weight-transpose loops with batched global loads + rowmax tree trimmed
# speedup vs baseline: 1.0146x; 1.0146x over previous
; #define LDS_WAIT() asm volatile("s_waitcnt lgkmcnt(0)" ::: "memory")
; __device__ __forceinline__ float wval(KArg ka, int mat, int l, int k, int n) {
;     ...
;     case M_BR:   { const int nb = n >> 10, d = n & 1023; return PIN(I_WBR)[(((size_t)l * 3 + nb) * 512 + k) * 1024 + d]; }
;     case M_OUT:  return PIN(I_WOUT)[((size_t)l * 1024 + k) * 1024 + n];
;     case M_GU:   { const int pn = n >> 8, half = (n >> 7) & 1, j = n & 127; const int src = half * DFF + pn * 128 + j; return PIN(I_WGU)[((size_t)l * 1024 + k) * 5632 + src] * PIN(I_LFPRE)[l * 1024 + k]; }
;     case M_DOWN: return PIN(I_WDOWN)[((size_t)l * DFF + k) * 1024 + n];
; __device__ __forceinline__ void tr_item(KArg ka, int mat, int l, int K, bf16_t* WT, LAS float* scr, int kb, int nb, int lane) {
;     const int k0 = 64 * kb, n0 = 32 * nb;
; #pragma unroll 4
;     for (int i = 0; i < 32; ++i) { const int kk = 2 * i + (lane >> 5); scr[kk * 33 + (lane & 31)] = wval(ka, mat, l, k0 + kk, n0 + (lane & 31)); }
;     LDS_WAIT(); asm volatile("" ::: "memory");
.LBB0_20:
	v_lshl_add_u64 v[22:23], v[20:21], 0, s[38:39]
	global_load_dword v48, v[22:23], off
	v_lshl_add_u64 v[22:23], v[18:19], 0, s[38:39]
	v_ashrrev_i32_e32 v15, 31, v14
	global_load_dword v49, v[22:23], off
	v_lshl_add_u64 v[22:23], v[16:17], 0, s[38:39]
	s_add_u32 s38, s38, 0x8000
	s_addc_u32 s39, s39, 0
	s_cmp_lg_u32 s38, 0x40000
	global_load_dword v50, v[22:23], off
	v_lshl_add_u64 v[22:23], s[4:5], 0, v[14:15]
	v_lshlrev_b64 v[22:23], 12, v[22:23]
	v_lshl_add_u64 v[22:23], v[12:13], 0, v[22:23]
	v_add_u32_e32 v14, 8, v14
	global_load_dword v51, v[22:23], off
	v_lshl_add_u64 v[22:23], v[20:21], 0, s[38:39]
	global_load_dword v52, v[22:23], off
	v_lshl_add_u64 v[22:23], v[18:19], 0, s[38:39]
	v_ashrrev_i32_e32 v15, 31, v14
	global_load_dword v53, v[22:23], off
	v_lshl_add_u64 v[22:23], v[16:17], 0, s[38:39]
	s_add_u32 s38, s38, 0x8000
	s_addc_u32 s39, s39, 0
	s_cmp_lg_u32 s38, 0x40000
	global_load_dword v54, v[22:23], off
	v_lshl_add_u64 v[22:23], s[4:5], 0, v[14:15]
	v_lshlrev_b64 v[22:23], 12, v[22:23]
	v_lshl_add_u64 v[22:23], v[12:13], 0, v[22:23]
	v_add_u32_e32 v14, 8, v14
	global_load_dword v55, v[22:23], off
	v_lshl_add_u64 v[22:23], v[20:21], 0, s[38:39]
	global_load_dword v56, v[22:23], off
	v_lshl_add_u64 v[22:23], v[18:19], 0, s[38:39]
	v_ashrrev_i32_e32 v15, 31, v14
	global_load_dword v57, v[22:23], off
	v_lshl_add_u64 v[22:23], v[16:17], 0, s[38:39]
	s_add_u32 s38, s38, 0x8000
	s_addc_u32 s39, s39, 0
	s_cmp_lg_u32 s38, 0x40000
	global_load_dword v58, v[22:23], off
	v_lshl_add_u64 v[22:23], s[4:5], 0, v[14:15]
	v_lshlrev_b64 v[22:23], 12, v[22:23]
	v_lshl_add_u64 v[22:23], v[12:13], 0, v[22:23]
	v_add_u32_e32 v14, 8, v14
	global_load_dword v59, v[22:23], off
	v_lshl_add_u64 v[22:23], v[20:21], 0, s[38:39]
	global_load_dword v60, v[22:23], off
	v_lshl_add_u64 v[22:23], v[18:19], 0, s[38:39]
	v_ashrrev_i32_e32 v15, 31, v14
	global_load_dword v61, v[22:23], off
	v_lshl_add_u64 v[22:23], v[16:17], 0, s[38:39]
	s_add_u32 s38, s38, 0x8000
	s_addc_u32 s39, s39, 0
	s_cmp_lg_u32 s38, 0x40000
	global_load_dword v62, v[22:23], off
	v_lshl_add_u64 v[22:23], s[4:5], 0, v[14:15]
	v_lshlrev_b64 v[22:23], 12, v[22:23]
	v_lshl_add_u64 v[22:23], v[12:13], 0, v[22:23]
	v_add_u32_e32 v14, 8, v14
	global_load_dword v63, v[22:23], off
	v_lshl_add_u64 v[22:23], v[20:21], 0, s[38:39]
	global_load_dword v64, v[22:23], off
	v_lshl_add_u64 v[22:23], v[18:19], 0, s[38:39]
	v_ashrrev_i32_e32 v15, 31, v14
	global_load_dword v65, v[22:23], off
	v_lshl_add_u64 v[22:23], v[16:17], 0, s[38:39]
	s_add_u32 s38, s38, 0x8000
	s_addc_u32 s39, s39, 0
	s_cmp_lg_u32 s38, 0x40000
	global_load_dword v66, v[22:23], off
	v_lshl_add_u64 v[22:23], s[4:5], 0, v[14:15]
	v_lshlrev_b64 v[22:23], 12, v[22:23]
	v_lshl_add_u64 v[22:23], v[12:13], 0, v[22:23]
	v_add_u32_e32 v14, 8, v14
	global_load_dword v67, v[22:23], off
	v_lshl_add_u64 v[22:23], v[20:21], 0, s[38:39]
	global_load_dword v68, v[22:23], off
	v_lshl_add_u64 v[22:23], v[18:19], 0, s[38:39]
	v_ashrrev_i32_e32 v15, 31, v14
	global_load_dword v69, v[22:23], off
	v_lshl_add_u64 v[22:23], v[16:17], 0, s[38:39]
	s_add_u32 s38, s38, 0x8000
	s_addc_u32 s39, s39, 0
	s_cmp_lg_u32 s38, 0x40000
	global_load_dword v70, v[22:23], off
	v_lshl_add_u64 v[22:23], s[4:5], 0, v[14:15]
	v_lshlrev_b64 v[22:23], 12, v[22:23]
	v_lshl_add_u64 v[22:23], v[12:13], 0, v[22:23]
	v_add_u32_e32 v14, 8, v14
	global_load_dword v71, v[22:23], off
	v_lshl_add_u64 v[22:23], v[20:21], 0, s[38:39]
	global_load_dword v72, v[22:23], off
	v_lshl_add_u64 v[22:23], v[18:19], 0, s[38:39]
	v_ashrrev_i32_e32 v15, 31, v14
	global_load_dword v73, v[22:23], off
	v_lshl_add_u64 v[22:23], v[16:17], 0, s[38:39]
	s_add_u32 s38, s38, 0x8000
	s_addc_u32 s39, s39, 0
	s_cmp_lg_u32 s38, 0x40000
	global_load_dword v74, v[22:23], off
	v_lshl_add_u64 v[22:23], s[4:5], 0, v[14:15]
	v_lshlrev_b64 v[22:23], 12, v[22:23]
	v_lshl_add_u64 v[22:23], v[12:13], 0, v[22:23]
	v_add_u32_e32 v14, 8, v14
	global_load_dword v75, v[22:23], off
	v_lshl_add_u64 v[22:23], v[20:21], 0, s[38:39]
	global_load_dword v76, v[22:23], off
	v_lshl_add_u64 v[22:23], v[18:19], 0, s[38:39]
	v_ashrrev_i32_e32 v15, 31, v14
	global_load_dword v77, v[22:23], off
	v_lshl_add_u64 v[22:23], v[16:17], 0, s[38:39]
	s_add_u32 s38, s38, 0x8000
	s_addc_u32 s39, s39, 0
	s_cmp_lg_u32 s38, 0x40000
	global_load_dword v78, v[22:23], off
	v_lshl_add_u64 v[22:23], s[4:5], 0, v[14:15]
	v_lshlrev_b64 v[22:23], 12, v[22:23]
	v_lshl_add_u64 v[22:23], v[12:13], 0, v[22:23]
	v_add_u32_e32 v14, 8, v14
	global_load_dword v79, v[22:23], off
	s_waitcnt vmcnt(0)
	ds_write_b32 v6, v48
	ds_write_b32 v6, v49 offset:264
	ds_write_b32 v6, v50 offset:528
	ds_write_b32 v6, v51 offset:792
	ds_write_b32 v6, v52 offset:1056
	ds_write_b32 v6, v53 offset:1320
	ds_write_b32 v6, v54 offset:1584
	ds_write_b32 v6, v55 offset:1848
	ds_write_b32 v6, v56 offset:2112
	ds_write_b32 v6, v57 offset:2376
	ds_write_b32 v6, v58 offset:2640
	ds_write_b32 v6, v59 offset:2904
	ds_write_b32 v6, v60 offset:3168
	ds_write_b32 v6, v61 offset:3432
	ds_write_b32 v6, v62 offset:3696
	ds_write_b32 v6, v63 offset:3960
	ds_write_b32 v6, v64 offset:4224
	ds_write_b32 v6, v65 offset:4488
	ds_write_b32 v6, v66 offset:4752
	ds_write_b32 v6, v67 offset:5016
	ds_write_b32 v6, v68 offset:5280
	ds_write_b32 v6, v69 offset:5544
	ds_write_b32 v6, v70 offset:5808
	ds_write_b32 v6, v71 offset:6072
	ds_write_b32 v6, v72 offset:6336
	ds_write_b32 v6, v73 offset:6600
	ds_write_b32 v6, v74 offset:6864
	ds_write_b32 v6, v75 offset:7128
	ds_write_b32 v6, v76 offset:7392
	ds_write_b32 v6, v77 offset:7656
	ds_write_b32 v6, v78 offset:7920
	ds_write_b32 v6, v79 offset:8184
	v_add_u32_e32 v6, 0x2100, v6
	s_cbranch_scc1 .LBB0_20
; __device__ __forceinline__ unsigned cvt_pk_bf16(float lo, float hi) { unsigned r; asm volatile("v_cvt_pk_bf16_f32 %0, %1, %2" : "=v"(r) : "v"(lo), "v"(hi)); return r; }
; #define LAS __attribute__((address_space(3)))
; #define LDS_WAIT() asm volatile("s_waitcnt lgkmcnt(0)" ::: "memory")
; __device__ __forceinline__ void tr_item(KArg ka, int mat, int l, int K, bf16_t* WT, LAS float* scr, int kb, int nb, int lane) {
;     ...
;     const int c = lane & 7;
; #pragma unroll
;     for (int j = 0; j < 4; ++j) { const int n = (lane >> 3) + 8 * j; const LAS float* s = scr + (8 * c) * 33 + n;
;         u32x4 o; o.x = cvt_pk_bf16(s[0 * 33], s[1 * 33]); o.y = cvt_pk_bf16(s[2 * 33], s[3 * 33]); o.z = cvt_pk_bf16(s[4 * 33], s[5 * 33]); o.w = cvt_pk_bf16(s[6 * 33], s[7 * 33]);
;         *(u32x4*)(WT + (size_t)(n0 + n) * K + k0 + 8 * c) = o; }
;     LDS_WAIT(); asm volatile("" ::: "memory");
	s_lshl_b32 s4, s40, 1
	s_waitcnt lgkmcnt(0)
	s_add_u32 s4, s67, s4
	v_mov_b32_e32 v11, v7
	s_addc_u32 s5, s66, 0
	ds_read2_b32 v[12:13], v25 offset1:33
	v_lshl_add_u64 v[18:19], s[4:5], 0, v[10:11]
	s_waitcnt lgkmcnt(0)
	v_cvt_pk_bf16_f32 v12, v12, v13
	ds_read2_b32 v[14:15], v25 offset0:66 offset1:99
	v_add_u32_e32 v6, s12, v24
	v_lshl_add_u64 v[18:19], v[18:19], 0, s[16:17]
	s_waitcnt lgkmcnt(0)
	v_cvt_pk_bf16_f32 v13, v14, v15
	ds_read2_b32 v[14:15], v25 offset0:132 offset1:165
	v_mad_i64_i32 v[20:21], s[4:5], v6, s57, v[18:19]
	s_waitcnt lgkmcnt(0)
	v_cvt_pk_bf16_f32 v14, v14, v15
	ds_read2_b32 v[16:17], v25 offset0:198 offset1:231
	s_waitcnt lgkmcnt(0)
	v_cvt_pk_bf16_f32 v15, v16, v17
	flat_store_dwordx4 v[20:21], v[12:15]
	ds_read2_b32 v[12:13], v25 offset0:8 offset1:41
	v_add_u32_e32 v6, s12, v26
	s_waitcnt lgkmcnt(0)
	v_cvt_pk_bf16_f32 v12, v12, v13
	ds_read2_b32 v[14:15], v25 offset0:74 offset1:107
	s_waitcnt lgkmcnt(0)
	v_cvt_pk_bf16_f32 v13, v14, v15
	ds_read2_b32 v[14:15], v25 offset0:140 offset1:173
	v_mad_i64_i32 v[20:21], s[4:5], v6, s57, v[18:19]
	s_waitcnt lgkmcnt(0)
	v_cvt_pk_bf16_f32 v14, v14, v15
	ds_read2_b32 v[16:17], v25 offset0:206 offset1:239
	s_waitcnt lgkmcnt(0)
	v_cvt_pk_bf16_f32 v15, v16, v17
	flat_store_dwordx4 v[20:21], v[12:15]
	ds_read2_b32 v[12:13], v25 offset0:16 offset1:49
	v_add_u32_e32 v6, s12, v27
	s_waitcnt lgkmcnt(0)
	v_cvt_pk_bf16_f32 v12, v12, v13
	ds_read2_b32 v[14:15], v25 offset0:82 offset1:115
	s_waitcnt lgkmcnt(0)
	v_cvt_pk_bf16_f32 v13, v14, v15
	ds_read2_b32 v[14:15], v25 offset0:148 offset1:181
	v_mad_i64_i32 v[20:21], s[4:5], v6, s57, v[18:19]
	s_waitcnt lgkmcnt(0)
	v_cvt_pk_bf16_f32 v14, v14, v15
	ds_read2_b32 v[16:17], v25 offset0:214 offset1:247
	s_waitcnt lgkmcnt(0)
	v_cvt_pk_bf16_f32 v15, v16, v17
	flat_store_dwordx4 v[20:21], v[12:15]
	ds_read2_b32 v[12:13], v25 offset0:24 offset1:57
	v_add_u32_e32 v6, s12, v28
	s_waitcnt lgkmcnt(0)
	v_cvt_pk_bf16_f32 v12, v12, v13
	ds_read2_b32 v[14:15], v25 offset0:90 offset1:123
	s_waitcnt lgkmcnt(0)
	v_cvt_pk_bf16_f32 v13, v14, v15
	ds_read2_b32 v[14:15], v25 offset0:156 offset1:189
	s_waitcnt lgkmcnt(0)
	v_cvt_pk_bf16_f32 v14, v14, v15
	ds_read2_b32 v[16:17], v25 offset0:222 offset1:255
	s_waitcnt lgkmcnt(0)
	v_cvt_pk_bf16_f32 v15, v16, v17
	v_mad_i64_i32 v[16:17], s[4:5], v6, s57, v[18:19]
	flat_store_dwordx4 v[16:17], v[12:15]
	s_waitcnt lgkmcnt(0)
	s_mov_b64 s[4:5], 0

; __device__ __forceinline__ float wval(KArg ka, int mat, int l, int k, int n) {
;     ...
;     case M_GU:   { const int pn = n >> 8, half = (n >> 7) & 1, j = n & 127; const int src = half * DFF + pn * 128 + j; return PIN(I_WGU)[((size_t)l * 1024 + k) * 5632 + src] * PIN(I_LFPRE)[l * 1024 + k]; }
; __device__ __forceinline__ void tr_item(KArg ka, int mat, int l, int K, bf16_t* WT, LAS float* scr, int kb, int nb, int lane) {
;     const int k0 = 64 * kb, n0 = 32 * nb;
; #pragma unroll 4
;     for (int i = 0; i < 32; ++i) { const int kk = 2 * i + (lane >> 5); scr[kk * 33 + (lane & 31)] = wval(ka, mat, l, k0 + kk, n0 + (lane & 31)); }
.LBB0_24:
	v_lshl_add_u64 v[40:41], v[22:23], 0, s[4:5]
	global_load_dword v48, v[20:21], off
	global_load_dword v49, v[40:41], off
	v_lshl_add_u64 v[40:41], v[16:17], 0, s[4:5]
	v_add_co_u32_e32 v42, vcc, -16, v18
	v_lshl_add_u64 v[20:21], v[20:21], 0, 32
	s_nop 0
	v_addc_co_u32_e32 v43, vcc, -1, v19, vcc
	global_load_dword v50, v[40:41], off
	global_load_dword v51, v[42:43], off
	v_lshl_add_u64 v[40:41], v[14:15], 0, s[4:5]
	v_add_co_u32_e32 v42, vcc, -8, v18
	v_addc_co_u32_e32 v43, vcc, -1, v19, vcc
	global_load_dword v52, v[40:41], off
	s_nop 0
	global_load_dword v53, v[42:43], off
	v_lshl_add_u64 v[40:41], v[12:13], 0, s[4:5]
	s_add_u32 s4, s4, 0x2c000
	s_addc_u32 s5, s5, 0
	s_cmp_lg_u32 s4, 0x160000
	global_load_dword v54, v[40:41], off
	s_nop 0
	global_load_dword v55, v[18:19], off
	v_lshl_add_u64 v[18:19], v[18:19], 0, 32
	v_lshl_add_u64 v[40:41], v[22:23], 0, s[4:5]
	global_load_dword v56, v[20:21], off
	global_load_dword v57, v[40:41], off
	v_lshl_add_u64 v[40:41], v[16:17], 0, s[4:5]
	v_add_co_u32_e32 v42, vcc, -16, v18
	v_lshl_add_u64 v[20:21], v[20:21], 0, 32
	s_nop 0
	v_addc_co_u32_e32 v43, vcc, -1, v19, vcc
	global_load_dword v58, v[40:41], off
	global_load_dword v59, v[42:43], off
	v_lshl_add_u64 v[40:41], v[14:15], 0, s[4:5]
	v_add_co_u32_e32 v42, vcc, -8, v18
	v_addc_co_u32_e32 v43, vcc, -1, v19, vcc
	global_load_dword v60, v[40:41], off
	s_nop 0
	global_load_dword v61, v[42:43], off
	v_lshl_add_u64 v[40:41], v[12:13], 0, s[4:5]
	s_add_u32 s4, s4, 0x2c000
	s_addc_u32 s5, s5, 0
	s_cmp_lg_u32 s4, 0x160000
	global_load_dword v62, v[40:41], off
	s_nop 0
	global_load_dword v63, v[18:19], off
	v_lshl_add_u64 v[18:19], v[18:19], 0, 32
	v_lshl_add_u64 v[40:41], v[22:23], 0, s[4:5]
	global_load_dword v64, v[20:21], off
	global_load_dword v65, v[40:41], off
	v_lshl_add_u64 v[40:41], v[16:17], 0, s[4:5]
	v_add_co_u32_e32 v42, vcc, -16, v18
	v_lshl_add_u64 v[20:21], v[20:21], 0, 32
	s_nop 0
	v_addc_co_u32_e32 v43, vcc, -1, v19, vcc
	global_load_dword v66, v[40:41], off
	global_load_dword v67, v[42:43], off
	v_lshl_add_u64 v[40:41], v[14:15], 0, s[4:5]
	v_add_co_u32_e32 v42, vcc, -8, v18
	v_addc_co_u32_e32 v43, vcc, -1, v19, vcc
	global_load_dword v68, v[40:41], off
	s_nop 0
	global_load_dword v69, v[42:43], off
	v_lshl_add_u64 v[40:41], v[12:13], 0, s[4:5]
	s_add_u32 s4, s4, 0x2c000
	s_addc_u32 s5, s5, 0
	s_cmp_lg_u32 s4, 0x160000
	global_load_dword v70, v[40:41], off
	s_nop 0
	global_load_dword v71, v[18:19], off
	v_lshl_add_u64 v[18:19], v[18:19], 0, 32
	v_lshl_add_u64 v[40:41], v[22:23], 0, s[4:5]
	global_load_dword v72, v[20:21], off
	global_load_dword v73, v[40:41], off
	v_lshl_add_u64 v[40:41], v[16:17], 0, s[4:5]
	v_add_co_u32_e32 v42, vcc, -16, v18
	v_lshl_add_u64 v[20:21], v[20:21], 0, 32
	s_nop 0
	v_addc_co_u32_e32 v43, vcc, -1, v19, vcc
	global_load_dword v74, v[40:41], off
	global_load_dword v75, v[42:43], off
	v_lshl_add_u64 v[40:41], v[14:15], 0, s[4:5]
	v_add_co_u32_e32 v42, vcc, -8, v18
	v_addc_co_u32_e32 v43, vcc, -1, v19, vcc
	global_load_dword v76, v[40:41], off
	s_nop 0
	global_load_dword v77, v[42:43], off
	v_lshl_add_u64 v[40:41], v[12:13], 0, s[4:5]
	s_add_u32 s4, s4, 0x2c000
	s_addc_u32 s5, s5, 0
	s_cmp_lg_u32 s4, 0x160000
	global_load_dword v78, v[40:41], off
	s_nop 0
	global_load_dword v79, v[18:19], off
	v_lshl_add_u64 v[18:19], v[18:19], 0, 32
	v_lshl_add_u64 v[40:41], v[22:23], 0, s[4:5]
	global_load_dword v80, v[20:21], off
	global_load_dword v81, v[40:41], off
	v_lshl_add_u64 v[40:41], v[16:17], 0, s[4:5]
	v_add_co_u32_e32 v42, vcc, -16, v18
	v_lshl_add_u64 v[20:21], v[20:21], 0, 32
	s_nop 0
	v_addc_co_u32_e32 v43, vcc, -1, v19, vcc
	global_load_dword v82, v[40:41], off
	global_load_dword v83, v[42:43], off
	v_lshl_add_u64 v[40:41], v[14:15], 0, s[4:5]
	v_add_co_u32_e32 v42, vcc, -8, v18
	v_addc_co_u32_e32 v43, vcc, -1, v19, vcc
	global_load_dword v84, v[40:41], off
	s_nop 0
	global_load_dword v85, v[42:43], off
	v_lshl_add_u64 v[40:41], v[12:13], 0, s[4:5]
	s_add_u32 s4, s4, 0x2c000
	s_addc_u32 s5, s5, 0
	s_cmp_lg_u32 s4, 0x160000
	global_load_dword v86, v[40:41], off
	s_nop 0
	global_load_dword v87, v[18:19], off
	v_lshl_add_u64 v[18:19], v[18:19], 0, 32
	v_lshl_add_u64 v[40:41], v[22:23], 0, s[4:5]
	global_load_dword v88, v[20:21], off
	global_load_dword v89, v[40:41], off
	v_lshl_add_u64 v[40:41], v[16:17], 0, s[4:5]
	v_add_co_u32_e32 v42, vcc, -16, v18
	v_lshl_add_u64 v[20:21], v[20:21], 0, 32
	s_nop 0
	v_addc_co_u32_e32 v43, vcc, -1, v19, vcc
	global_load_dword v90, v[40:41], off
	global_load_dword v91, v[42:43], off
	v_lshl_add_u64 v[40:41], v[14:15], 0, s[4:5]
	v_add_co_u32_e32 v42, vcc, -8, v18
	v_addc_co_u32_e32 v43, vcc, -1, v19, vcc
	global_load_dword v92, v[40:41], off
	s_nop 0
	global_load_dword v93, v[42:43], off
	v_lshl_add_u64 v[40:41], v[12:13], 0, s[4:5]
	s_add_u32 s4, s4, 0x2c000
	s_addc_u32 s5, s5, 0
	s_cmp_lg_u32 s4, 0x160000
	global_load_dword v94, v[40:41], off
	s_nop 0
	global_load_dword v95, v[18:19], off
	v_lshl_add_u64 v[18:19], v[18:19], 0, 32
	v_lshl_add_u64 v[40:41], v[22:23], 0, s[4:5]
	global_load_dword v96, v[20:21], off
	global_load_dword v97, v[40:41], off
	v_lshl_add_u64 v[40:41], v[16:17], 0, s[4:5]
	v_add_co_u32_e32 v42, vcc, -16, v18
	v_lshl_add_u64 v[20:21], v[20:21], 0, 32
	s_nop 0
	v_addc_co_u32_e32 v43, vcc, -1, v19, vcc
	global_load_dword v98, v[40:41], off
	global_load_dword v99, v[42:43], off
	v_lshl_add_u64 v[40:41], v[14:15], 0, s[4:5]
	v_add_co_u32_e32 v42, vcc, -8, v18
	v_addc_co_u32_e32 v43, vcc, -1, v19, vcc
	global_load_dword v100, v[40:41], off
	s_nop 0
	global_load_dword v101, v[42:43], off
	v_lshl_add_u64 v[40:41], v[12:13], 0, s[4:5]
	s_add_u32 s4, s4, 0x2c000
	s_addc_u32 s5, s5, 0
	s_cmp_lg_u32 s4, 0x160000
	global_load_dword v102, v[40:41], off
	s_nop 0
	global_load_dword v103, v[18:19], off
	v_lshl_add_u64 v[18:19], v[18:19], 0, 32
	v_lshl_add_u64 v[40:41], v[22:23], 0, s[4:5]
	global_load_dword v104, v[20:21], off
	global_load_dword v105, v[40:41], off
	v_lshl_add_u64 v[40:41], v[16:17], 0, s[4:5]
	v_add_co_u32_e32 v42, vcc, -16, v18
	v_lshl_add_u64 v[20:21], v[20:21], 0, 32
	s_nop 0
	v_addc_co_u32_e32 v43, vcc, -1, v19, vcc
	global_load_dword v106, v[40:41], off
	global_load_dword v107, v[42:43], off
	v_lshl_add_u64 v[40:41], v[14:15], 0, s[4:5]
	v_add_co_u32_e32 v42, vcc, -8, v18
	v_addc_co_u32_e32 v43, vcc, -1, v19, vcc
	global_load_dword v108, v[40:41], off
	s_nop 0
	global_load_dword v109, v[42:43], off
	v_lshl_add_u64 v[40:41], v[12:13], 0, s[4:5]
	s_add_u32 s4, s4, 0x2c000
	s_addc_u32 s5, s5, 0
	s_cmp_lg_u32 s4, 0x160000
	global_load_dword v110, v[40:41], off
	s_nop 0
	global_load_dword v111, v[18:19], off
	v_lshl_add_u64 v[18:19], v[18:19], 0, 32
	s_waitcnt vmcnt(0)
; __device__ __forceinline__ unsigned cvt_pk_bf16(float lo, float hi) { unsigned r; asm volatile("v_cvt_pk_bf16_f32 %0, %1, %2" : "=v"(r) : "v"(lo), "v"(hi)); return r; }
; #define LAS __attribute__((address_space(3)))
; #define LDS_WAIT() asm volatile("s_waitcnt lgkmcnt(0)" ::: "memory")
; __device__ __forceinline__ float wval(KArg ka, int mat, int l, int k, int n) {
;     ...
;     case M_GU:   { const int pn = n >> 8, half = (n >> 7) & 1, j = n & 127; const int src = half * DFF + pn * 128 + j; return PIN(I_WGU)[((size_t)l * 1024 + k) * 5632 + src] * PIN(I_LFPRE)[l * 1024 + k]; }
; __device__ __forceinline__ void tr_item(KArg ka, int mat, int l, int K, bf16_t* WT, LAS float* scr, int kb, int nb, int lane) {
;     ...
;     for (int i = 0; i < 32; ++i) { const int kk = 2 * i + (lane >> 5); scr[kk * 33 + (lane & 31)] = wval(ka, mat, l, k0 + kk, n0 + (lane & 31)); }
;     LDS_WAIT(); asm volatile("" ::: "memory");
;     const int c = lane & 7;
; #pragma unroll
;     for (int j = 0; j < 4; ++j) { const int n = (lane >> 3) + 8 * j; const LAS float* s = scr + (8 * c) * 33 + n;
;         u32x4 o; o.x = cvt_pk_bf16(s[0 * 33], s[1 * 33]); o.y = cvt_pk_bf16(s[2 * 33], s[3 * 33]); o.z = cvt_pk_bf16(s[4 * 33], s[5 * 33]); o.w = cvt_pk_bf16(s[6 * 33], s[7 * 33]);
;         *(u32x4*)(WT + (size_t)(n0 + n) * K + k0 + 8 * c) = o; }
;     LDS_WAIT(); asm volatile("" ::: "memory");
	v_mul_f32_e32 v48, v49, v48
	ds_write_b32 v6, v48
	v_mul_f32_e32 v51, v50, v51
	ds_write_b32 v6, v51 offset:264
	v_mul_f32_e32 v53, v52, v53
	ds_write_b32 v6, v53 offset:528
	v_mul_f32_e32 v55, v54, v55
	ds_write_b32 v6, v55 offset:792
	v_mul_f32_e32 v56, v57, v56
	ds_write_b32 v6, v56 offset:1056
	v_mul_f32_e32 v59, v58, v59
	ds_write_b32 v6, v59 offset:1320
	v_mul_f32_e32 v61, v60, v61
	ds_write_b32 v6, v61 offset:1584
	v_mul_f32_e32 v63, v62, v63
	ds_write_b32 v6, v63 offset:1848
	v_mul_f32_e32 v64, v65, v64
	ds_write_b32 v6, v64 offset:2112
	v_mul_f32_e32 v67, v66, v67
	ds_write_b32 v6, v67 offset:2376
	v_mul_f32_e32 v69, v68, v69
	ds_write_b32 v6, v69 offset:2640
	v_mul_f32_e32 v71, v70, v71
	ds_write_b32 v6, v71 offset:2904
	v_mul_f32_e32 v72, v73, v72
	ds_write_b32 v6, v72 offset:3168
	v_mul_f32_e32 v75, v74, v75
	ds_write_b32 v6, v75 offset:3432
	v_mul_f32_e32 v77, v76, v77
	ds_write_b32 v6, v77 offset:3696
	v_mul_f32_e32 v79, v78, v79
	ds_write_b32 v6, v79 offset:3960
	v_mul_f32_e32 v80, v81, v80
	ds_write_b32 v6, v80 offset:4224
	v_mul_f32_e32 v83, v82, v83
	ds_write_b32 v6, v83 offset:4488
	v_mul_f32_e32 v85, v84, v85
	ds_write_b32 v6, v85 offset:4752
	v_mul_f32_e32 v87, v86, v87
	ds_write_b32 v6, v87 offset:5016
	v_mul_f32_e32 v88, v89, v88
	ds_write_b32 v6, v88 offset:5280
	v_mul_f32_e32 v91, v90, v91
	ds_write_b32 v6, v91 offset:5544
	v_mul_f32_e32 v93, v92, v93
	ds_write_b32 v6, v93 offset:5808
	v_mul_f32_e32 v95, v94, v95
	ds_write_b32 v6, v95 offset:6072
	v_mul_f32_e32 v96, v97, v96
	ds_write_b32 v6, v96 offset:6336
	v_mul_f32_e32 v99, v98, v99
	ds_write_b32 v6, v99 offset:6600
	v_mul_f32_e32 v101, v100, v101
	ds_write_b32 v6, v101 offset:6864
	v_mul_f32_e32 v103, v102, v103
	ds_write_b32 v6, v103 offset:7128
	v_mul_f32_e32 v104, v105, v104
	ds_write_b32 v6, v104 offset:7392
	v_mul_f32_e32 v107, v106, v107
	ds_write_b32 v6, v107 offset:7656
	v_mul_f32_e32 v109, v108, v109
	ds_write_b32 v6, v109 offset:7920
	v_mul_f32_e32 v111, v110, v111
	ds_write_b32 v6, v111 offset:8184
	v_add_u32_e32 v6, 0x2100, v6
	s_cbranch_scc1 .LBB0_24
	s_and_b32 s4, 0xffff, s38
	s_waitcnt lgkmcnt(0)
	s_lshl_b32 s4, s4, 1
	s_add_u32 s4, s67, s4
	ds_read2_b32 v[12:13], v25 offset1:33
	v_mov_b32_e32 v11, v7
	v_add_u32_e32 v16, s12, v24
	s_addc_u32 s5, s66, 0
	s_waitcnt lgkmcnt(0)
	v_cvt_pk_bf16_f32 v12, v12, v13
	ds_read2_b32 v[14:15], v25 offset0:66 offset1:99
	v_ashrrev_i32_e32 v17, 31, v16
	v_lshl_add_u64 v[20:21], s[4:5], 0, v[10:11]
	s_waitcnt lgkmcnt(0)
	v_cvt_pk_bf16_f32 v13, v14, v15
	ds_read2_b32 v[14:15], v25 offset0:132 offset1:165
	v_lshlrev_b64 v[16:17], 11, v[16:17]
	v_lshl_add_u64 v[20:21], v[20:21], 0, s[18:19]
	s_waitcnt lgkmcnt(0)
	v_cvt_pk_bf16_f32 v14, v14, v15
	ds_read2_b32 v[18:19], v25 offset0:198 offset1:231
	v_lshl_add_u64 v[16:17], v[20:21], 0, v[16:17]
	s_waitcnt lgkmcnt(0)
	v_cvt_pk_bf16_f32 v15, v18, v19
	flat_store_dwordx4 v[16:17], v[12:15]
	v_add_u32_e32 v18, s12, v26
	ds_read2_b32 v[12:13], v25 offset0:8 offset1:41
	v_ashrrev_i32_e32 v19, 31, v18
	s_waitcnt lgkmcnt(0)
	v_cvt_pk_bf16_f32 v12, v12, v13
	ds_read2_b32 v[14:15], v25 offset0:74 offset1:107
	v_lshlrev_b64 v[18:19], 11, v[18:19]
	s_waitcnt lgkmcnt(0)
	v_cvt_pk_bf16_f32 v13, v14, v15
	ds_read2_b32 v[14:15], v25 offset0:140 offset1:173
	v_lshl_add_u64 v[18:19], v[20:21], 0, v[18:19]
	s_waitcnt lgkmcnt(0)
	v_cvt_pk_bf16_f32 v14, v14, v15
	ds_read2_b32 v[16:17], v25 offset0:206 offset1:239
	s_waitcnt lgkmcnt(0)
	v_cvt_pk_bf16_f32 v15, v16, v17
	flat_store_dwordx4 v[18:19], v[12:15]
	v_add_u32_e32 v18, s12, v27
	ds_read2_b32 v[12:13], v25 offset0:16 offset1:49
	v_ashrrev_i32_e32 v19, 31, v18
	s_waitcnt lgkmcnt(0)
	v_cvt_pk_bf16_f32 v12, v12, v13
	ds_read2_b32 v[14:15], v25 offset0:82 offset1:115
	v_lshlrev_b64 v[18:19], 11, v[18:19]
	s_waitcnt lgkmcnt(0)
	v_cvt_pk_bf16_f32 v13, v14, v15
	ds_read2_b32 v[14:15], v25 offset0:148 offset1:181
	v_lshl_add_u64 v[18:19], v[20:21], 0, v[18:19]
	s_waitcnt lgkmcnt(0)
	v_cvt_pk_bf16_f32 v14, v14, v15
	ds_read2_b32 v[16:17], v25 offset0:214 offset1:247
	s_waitcnt lgkmcnt(0)
	v_cvt_pk_bf16_f32 v15, v16, v17
	flat_store_dwordx4 v[18:19], v[12:15]
	ds_read2_b32 v[12:13], v25 offset0:24 offset1:57
	v_add_u32_e32 v18, s12, v28
	s_waitcnt lgkmcnt(0)
	v_cvt_pk_bf16_f32 v12, v12, v13
	ds_read2_b32 v[14:15], v25 offset0:90 offset1:123
	s_waitcnt lgkmcnt(0)
	v_cvt_pk_bf16_f32 v13, v14, v15
	ds_read2_b32 v[14:15], v25 offset0:156 offset1:189
	v_ashrrev_i32_e32 v19, 31, v18
	s_waitcnt lgkmcnt(0)
	v_cvt_pk_bf16_f32 v14, v14, v15
	ds_read2_b32 v[16:17], v25 offset0:222 offset1:255
	v_lshlrev_b64 v[18:19], 11, v[18:19]
	s_waitcnt lgkmcnt(0)
	v_cvt_pk_bf16_f32 v15, v16, v17
	v_lshl_add_u64 v[16:17], v[20:21], 0, v[18:19]
	flat_store_dwordx4 v[16:17], v[12:15]
	s_waitcnt lgkmcnt(0)

; #define LDS_WAIT() asm volatile("s_waitcnt lgkmcnt(0)" ::: "memory")
; __device__ __forceinline__ float wval(KArg ka, int mat, int l, int k, int n) {
;     ...
;     case M_OUT:  return PIN(I_WOUT)[((size_t)l * 1024 + k) * 1024 + n];
; __device__ __forceinline__ void tr_item(KArg ka, int mat, int l, int K, bf16_t* WT, LAS float* scr, int kb, int nb, int lane) {
;     const int k0 = 64 * kb, n0 = 32 * nb;
; #pragma unroll 4
;     for (int i = 0; i < 32; ++i) { const int kk = 2 * i + (lane >> 5); scr[kk * 33 + (lane & 31)] = wval(ka, mat, l, k0 + kk, n0 + (lane & 31)); }
;     LDS_WAIT(); asm volatile("" ::: "memory");
.LBB0_29:
	v_lshl_add_u64 v[22:23], v[20:21], 0, s[4:5]
	global_load_dword v48, v[22:23], off
	v_lshl_add_u64 v[22:23], v[18:19], 0, s[4:5]
	v_ashrrev_i32_e32 v15, 31, v14
	global_load_dword v49, v[22:23], off
	v_lshl_add_u64 v[22:23], v[16:17], 0, s[4:5]
	s_add_u32 s4, s4, 0x8000
	s_addc_u32 s5, s5, 0
	s_cmp_lg_u32 s4, 0x40000
	global_load_dword v50, v[22:23], off
	v_lshlrev_b64 v[22:23], 12, v[14:15]
	v_lshl_add_u64 v[22:23], v[12:13], 0, v[22:23]
	v_add_u32_e32 v14, 8, v14
	global_load_dword v51, v[22:23], off
	v_lshl_add_u64 v[22:23], v[20:21], 0, s[4:5]
	global_load_dword v52, v[22:23], off
	v_lshl_add_u64 v[22:23], v[18:19], 0, s[4:5]
	v_ashrrev_i32_e32 v15, 31, v14
	global_load_dword v53, v[22:23], off
	v_lshl_add_u64 v[22:23], v[16:17], 0, s[4:5]
	s_add_u32 s4, s4, 0x8000
	s_addc_u32 s5, s5, 0
	s_cmp_lg_u32 s4, 0x40000
	global_load_dword v54, v[22:23], off
	v_lshlrev_b64 v[22:23], 12, v[14:15]
	v_lshl_add_u64 v[22:23], v[12:13], 0, v[22:23]
	v_add_u32_e32 v14, 8, v14
	global_load_dword v55, v[22:23], off
	v_lshl_add_u64 v[22:23], v[20:21], 0, s[4:5]
	global_load_dword v56, v[22:23], off
	v_lshl_add_u64 v[22:23], v[18:19], 0, s[4:5]
	v_ashrrev_i32_e32 v15, 31, v14
	global_load_dword v57, v[22:23], off
	v_lshl_add_u64 v[22:23], v[16:17], 0, s[4:5]
	s_add_u32 s4, s4, 0x8000
	s_addc_u32 s5, s5, 0
	s_cmp_lg_u32 s4, 0x40000
	global_load_dword v58, v[22:23], off
	v_lshlrev_b64 v[22:23], 12, v[14:15]
	v_lshl_add_u64 v[22:23], v[12:13], 0, v[22:23]
	v_add_u32_e32 v14, 8, v14
	global_load_dword v59, v[22:23], off
	v_lshl_add_u64 v[22:23], v[20:21], 0, s[4:5]
	global_load_dword v60, v[22:23], off
	v_lshl_add_u64 v[22:23], v[18:19], 0, s[4:5]
	v_ashrrev_i32_e32 v15, 31, v14
	global_load_dword v61, v[22:23], off
	v_lshl_add_u64 v[22:23], v[16:17], 0, s[4:5]
	s_add_u32 s4, s4, 0x8000
	s_addc_u32 s5, s5, 0
	s_cmp_lg_u32 s4, 0x40000
	global_load_dword v62, v[22:23], off
	v_lshlrev_b64 v[22:23], 12, v[14:15]
	v_lshl_add_u64 v[22:23], v[12:13], 0, v[22:23]
	v_add_u32_e32 v14, 8, v14
	global_load_dword v63, v[22:23], off
	v_lshl_add_u64 v[22:23], v[20:21], 0, s[4:5]
	global_load_dword v64, v[22:23], off
	v_lshl_add_u64 v[22:23], v[18:19], 0, s[4:5]
	v_ashrrev_i32_e32 v15, 31, v14
	global_load_dword v65, v[22:23], off
	v_lshl_add_u64 v[22:23], v[16:17], 0, s[4:5]
	s_add_u32 s4, s4, 0x8000
	s_addc_u32 s5, s5, 0
	s_cmp_lg_u32 s4, 0x40000
	global_load_dword v66, v[22:23], off
	v_lshlrev_b64 v[22:23], 12, v[14:15]
	v_lshl_add_u64 v[22:23], v[12:13], 0, v[22:23]
	v_add_u32_e32 v14, 8, v14
	global_load_dword v67, v[22:23], off
	v_lshl_add_u64 v[22:23], v[20:21], 0, s[4:5]
	global_load_dword v68, v[22:23], off
	v_lshl_add_u64 v[22:23], v[18:19], 0, s[4:5]
	v_ashrrev_i32_e32 v15, 31, v14
	global_load_dword v69, v[22:23], off
	v_lshl_add_u64 v[22:23], v[16:17], 0, s[4:5]
	s_add_u32 s4, s4, 0x8000
	s_addc_u32 s5, s5, 0
	s_cmp_lg_u32 s4, 0x40000
	global_load_dword v70, v[22:23], off
	v_lshlrev_b64 v[22:23], 12, v[14:15]
	v_lshl_add_u64 v[22:23], v[12:13], 0, v[22:23]
	v_add_u32_e32 v14, 8, v14
	global_load_dword v71, v[22:23], off
	v_lshl_add_u64 v[22:23], v[20:21], 0, s[4:5]
	global_load_dword v72, v[22:23], off
	v_lshl_add_u64 v[22:23], v[18:19], 0, s[4:5]
	v_ashrrev_i32_e32 v15, 31, v14
	global_load_dword v73, v[22:23], off
	v_lshl_add_u64 v[22:23], v[16:17], 0, s[4:5]
	s_add_u32 s4, s4, 0x8000
	s_addc_u32 s5, s5, 0
	s_cmp_lg_u32 s4, 0x40000
	global_load_dword v74, v[22:23], off
	v_lshlrev_b64 v[22:23], 12, v[14:15]
	v_lshl_add_u64 v[22:23], v[12:13], 0, v[22:23]
	v_add_u32_e32 v14, 8, v14
	global_load_dword v75, v[22:23], off
	v_lshl_add_u64 v[22:23], v[20:21], 0, s[4:5]
	global_load_dword v76, v[22:23], off
	v_lshl_add_u64 v[22:23], v[18:19], 0, s[4:5]
	v_ashrrev_i32_e32 v15, 31, v14
	global_load_dword v77, v[22:23], off
	v_lshl_add_u64 v[22:23], v[16:17], 0, s[4:5]
	s_add_u32 s4, s4, 0x8000
	s_addc_u32 s5, s5, 0
	s_cmp_lg_u32 s4, 0x40000
	global_load_dword v78, v[22:23], off
	v_lshlrev_b64 v[22:23], 12, v[14:15]
	v_lshl_add_u64 v[22:23], v[12:13], 0, v[22:23]
	v_add_u32_e32 v14, 8, v14
	global_load_dword v79, v[22:23], off
	s_waitcnt vmcnt(0)
	ds_write_b32 v6, v48
	ds_write_b32 v6, v49 offset:264
	ds_write_b32 v6, v50 offset:528
	ds_write_b32 v6, v51 offset:792
	ds_write_b32 v6, v52 offset:1056
	ds_write_b32 v6, v53 offset:1320
	ds_write_b32 v6, v54 offset:1584
	ds_write_b32 v6, v55 offset:1848
	ds_write_b32 v6, v56 offset:2112
	ds_write_b32 v6, v57 offset:2376
	ds_write_b32 v6, v58 offset:2640
	ds_write_b32 v6, v59 offset:2904
	ds_write_b32 v6, v60 offset:3168
	ds_write_b32 v6, v61 offset:3432
	ds_write_b32 v6, v62 offset:3696
	ds_write_b32 v6, v63 offset:3960
	ds_write_b32 v6, v64 offset:4224
	ds_write_b32 v6, v65 offset:4488
	ds_write_b32 v6, v66 offset:4752
	ds_write_b32 v6, v67 offset:5016
	ds_write_b32 v6, v68 offset:5280
	ds_write_b32 v6, v69 offset:5544
	ds_write_b32 v6, v70 offset:5808
	ds_write_b32 v6, v71 offset:6072
	ds_write_b32 v6, v72 offset:6336
	ds_write_b32 v6, v73 offset:6600
	ds_write_b32 v6, v74 offset:6864
	ds_write_b32 v6, v75 offset:7128
	ds_write_b32 v6, v76 offset:7392
	ds_write_b32 v6, v77 offset:7656
	ds_write_b32 v6, v78 offset:7920
	ds_write_b32 v6, v79 offset:8184
	v_add_u32_e32 v6, 0x2100, v6
	s_cbranch_scc1 .LBB0_29
; __device__ __forceinline__ unsigned cvt_pk_bf16(float lo, float hi) { unsigned r; asm volatile("v_cvt_pk_bf16_f32 %0, %1, %2" : "=v"(r) : "v"(lo), "v"(hi)); return r; }
; #define LAS __attribute__((address_space(3)))
; #define LDS_WAIT() asm volatile("s_waitcnt lgkmcnt(0)" ::: "memory")
; __device__ __forceinline__ void tr_item(KArg ka, int mat, int l, int K, bf16_t* WT, LAS float* scr, int kb, int nb, int lane) {
;     ...
;     const int c = lane & 7;
; #pragma unroll
;     for (int j = 0; j < 4; ++j) { const int n = (lane >> 3) + 8 * j; const LAS float* s = scr + (8 * c) * 33 + n;
;         u32x4 o; o.x = cvt_pk_bf16(s[0 * 33], s[1 * 33]); o.y = cvt_pk_bf16(s[2 * 33], s[3 * 33]); o.z = cvt_pk_bf16(s[4 * 33], s[5 * 33]); o.w = cvt_pk_bf16(s[6 * 33], s[7 * 33]);
;         *(u32x4*)(WT + (size_t)(n0 + n) * K + k0 + 8 * c) = o; }
;     LDS_WAIT(); asm volatile("" ::: "memory");
	s_waitcnt lgkmcnt(0)
	s_lshl_b32 s4, s38, 1
	s_add_u32 s4, s67, s4
	ds_read2_b32 v[12:13], v25 offset1:33
	v_mov_b32_e32 v11, v7
	v_add_u32_e32 v16, s12, v24
	s_addc_u32 s5, s66, 0
	s_waitcnt lgkmcnt(0)
	v_cvt_pk_bf16_f32 v12, v12, v13
	ds_read2_b32 v[14:15], v25 offset0:66 offset1:99
	v_ashrrev_i32_e32 v17, 31, v16
	v_lshl_add_u64 v[20:21], s[4:5], 0, v[10:11]
	s_waitcnt lgkmcnt(0)
	v_cvt_pk_bf16_f32 v13, v14, v15
	ds_read2_b32 v[14:15], v25 offset0:132 offset1:165
	v_lshlrev_b64 v[16:17], 11, v[16:17]
	v_lshl_add_u64 v[20:21], v[20:21], 0, s[20:21]
	s_waitcnt lgkmcnt(0)
	v_cvt_pk_bf16_f32 v14, v14, v15
	ds_read2_b32 v[18:19], v25 offset0:198 offset1:231
	v_lshl_add_u64 v[16:17], v[20:21], 0, v[16:17]
	s_waitcnt lgkmcnt(0)
	v_cvt_pk_bf16_f32 v15, v18, v19
	flat_store_dwordx4 v[16:17], v[12:15]
	v_add_u32_e32 v18, s12, v26
	ds_read2_b32 v[12:13], v25 offset0:8 offset1:41
	v_ashrrev_i32_e32 v19, 31, v18
	s_waitcnt lgkmcnt(0)
	v_cvt_pk_bf16_f32 v12, v12, v13
	ds_read2_b32 v[14:15], v25 offset0:74 offset1:107
	v_lshlrev_b64 v[18:19], 11, v[18:19]
	s_waitcnt lgkmcnt(0)
	v_cvt_pk_bf16_f32 v13, v14, v15
	ds_read2_b32 v[14:15], v25 offset0:140 offset1:173
	v_lshl_add_u64 v[18:19], v[20:21], 0, v[18:19]
	s_waitcnt lgkmcnt(0)
	v_cvt_pk_bf16_f32 v14, v14, v15
	ds_read2_b32 v[16:17], v25 offset0:206 offset1:239
	s_waitcnt lgkmcnt(0)
	v_cvt_pk_bf16_f32 v15, v16, v17
	flat_store_dwordx4 v[18:19], v[12:15]
	v_add_u32_e32 v18, s12, v27
	ds_read2_b32 v[12:13], v25 offset0:16 offset1:49
	v_ashrrev_i32_e32 v19, 31, v18
	s_waitcnt lgkmcnt(0)
	v_cvt_pk_bf16_f32 v12, v12, v13
	ds_read2_b32 v[14:15], v25 offset0:82 offset1:115
	v_lshlrev_b64 v[18:19], 11, v[18:19]
	s_waitcnt lgkmcnt(0)
	v_cvt_pk_bf16_f32 v13, v14, v15
	ds_read2_b32 v[14:15], v25 offset0:148 offset1:181
	v_lshl_add_u64 v[18:19], v[20:21], 0, v[18:19]
	s_waitcnt lgkmcnt(0)
	v_cvt_pk_bf16_f32 v14, v14, v15
	ds_read2_b32 v[16:17], v25 offset0:214 offset1:247
	s_waitcnt lgkmcnt(0)
	v_cvt_pk_bf16_f32 v15, v16, v17
	flat_store_dwordx4 v[18:19], v[12:15]
	ds_read2_b32 v[12:13], v25 offset0:24 offset1:57
	v_add_u32_e32 v18, s12, v28
	s_waitcnt lgkmcnt(0)
	v_cvt_pk_bf16_f32 v12, v12, v13
	ds_read2_b32 v[14:15], v25 offset0:90 offset1:123
	s_waitcnt lgkmcnt(0)
	v_cvt_pk_bf16_f32 v13, v14, v15
	ds_read2_b32 v[14:15], v25 offset0:156 offset1:189
	v_ashrrev_i32_e32 v19, 31, v18
	s_waitcnt lgkmcnt(0)
	v_cvt_pk_bf16_f32 v14, v14, v15
	ds_read2_b32 v[16:17], v25 offset0:222 offset1:255
	v_lshlrev_b64 v[18:19], 11, v[18:19]
	s_waitcnt lgkmcnt(0)
	v_cvt_pk_bf16_f32 v15, v16, v17
	v_lshl_add_u64 v[16:17], v[20:21], 0, v[18:19]
	flat_store_dwordx4 v[16:17], v[12:15]
	s_waitcnt lgkmcnt(0)

; #define LDS_WAIT() asm volatile("s_waitcnt lgkmcnt(0)" ::: "memory")
; __device__ __forceinline__ float wval(KArg ka, int mat, int l, int k, int n) {
;     ...
;     case M_BR:   { const int nb = n >> 10, d = n & 1023; return PIN(I_WBR)[(((size_t)l * 3 + nb) * 512 + k) * 1024 + d]; }
; __device__ __forceinline__ void tr_item(KArg ka, int mat, int l, int K, bf16_t* WT, LAS float* scr, int kb, int nb, int lane) {
;     const int k0 = 64 * kb, n0 = 32 * nb;
; #pragma unroll 4
;     for (int i = 0; i < 32; ++i) { const int kk = 2 * i + (lane >> 5); scr[kk * 33 + (lane & 31)] = wval(ka, mat, l, k0 + kk, n0 + (lane & 31)); }
;     LDS_WAIT(); asm volatile("" ::: "memory");
.LBB0_34:
	v_lshl_add_u64 v[20:21], v[18:19], 0, s[4:5]
	global_load_dword v48, v[20:21], off
	v_lshl_add_u64 v[20:21], v[16:17], 0, s[4:5]
	global_load_dword v49, v[20:21], off
	v_lshl_add_u64 v[20:21], v[14:15], 0, s[4:5]
	global_load_dword v50, v[20:21], off
	v_lshl_add_u64 v[20:21], v[12:13], 0, s[4:5]
	s_add_u32 s4, s4, 0x8000
	s_addc_u32 s5, s5, 0
	s_cmp_lg_u32 s4, 0x40000
	global_load_dword v51, v[20:21], off
	v_lshl_add_u64 v[20:21], v[18:19], 0, s[4:5]
	global_load_dword v52, v[20:21], off
	v_lshl_add_u64 v[20:21], v[16:17], 0, s[4:5]
	global_load_dword v53, v[20:21], off
	v_lshl_add_u64 v[20:21], v[14:15], 0, s[4:5]
	global_load_dword v54, v[20:21], off
	v_lshl_add_u64 v[20:21], v[12:13], 0, s[4:5]
	s_add_u32 s4, s4, 0x8000
	s_addc_u32 s5, s5, 0
	s_cmp_lg_u32 s4, 0x40000
	global_load_dword v55, v[20:21], off
	v_lshl_add_u64 v[20:21], v[18:19], 0, s[4:5]
	global_load_dword v56, v[20:21], off
	v_lshl_add_u64 v[20:21], v[16:17], 0, s[4:5]
	global_load_dword v57, v[20:21], off
	v_lshl_add_u64 v[20:21], v[14:15], 0, s[4:5]
	global_load_dword v58, v[20:21], off
	v_lshl_add_u64 v[20:21], v[12:13], 0, s[4:5]
	s_add_u32 s4, s4, 0x8000
	s_addc_u32 s5, s5, 0
	s_cmp_lg_u32 s4, 0x40000
	global_load_dword v59, v[20:21], off
	v_lshl_add_u64 v[20:21], v[18:19], 0, s[4:5]
	global_load_dword v60, v[20:21], off
	v_lshl_add_u64 v[20:21], v[16:17], 0, s[4:5]
	global_load_dword v61, v[20:21], off
	v_lshl_add_u64 v[20:21], v[14:15], 0, s[4:5]
	global_load_dword v62, v[20:21], off
	v_lshl_add_u64 v[20:21], v[12:13], 0, s[4:5]
	s_add_u32 s4, s4, 0x8000
	s_addc_u32 s5, s5, 0
	s_cmp_lg_u32 s4, 0x40000
	global_load_dword v63, v[20:21], off
	v_lshl_add_u64 v[20:21], v[18:19], 0, s[4:5]
	global_load_dword v64, v[20:21], off
	v_lshl_add_u64 v[20:21], v[16:17], 0, s[4:5]
	global_load_dword v65, v[20:21], off
	v_lshl_add_u64 v[20:21], v[14:15], 0, s[4:5]
	global_load_dword v66, v[20:21], off
	v_lshl_add_u64 v[20:21], v[12:13], 0, s[4:5]
	s_add_u32 s4, s4, 0x8000
	s_addc_u32 s5, s5, 0
	s_cmp_lg_u32 s4, 0x40000
	global_load_dword v67, v[20:21], off
	v_lshl_add_u64 v[20:21], v[18:19], 0, s[4:5]
	global_load_dword v68, v[20:21], off
	v_lshl_add_u64 v[20:21], v[16:17], 0, s[4:5]
	global_load_dword v69, v[20:21], off
	v_lshl_add_u64 v[20:21], v[14:15], 0, s[4:5]
	global_load_dword v70, v[20:21], off
	v_lshl_add_u64 v[20:21], v[12:13], 0, s[4:5]
	s_add_u32 s4, s4, 0x8000
	s_addc_u32 s5, s5, 0
	s_cmp_lg_u32 s4, 0x40000
	global_load_dword v71, v[20:21], off
	v_lshl_add_u64 v[20:21], v[18:19], 0, s[4:5]
	global_load_dword v72, v[20:21], off
	v_lshl_add_u64 v[20:21], v[16:17], 0, s[4:5]
	global_load_dword v73, v[20:21], off
	v_lshl_add_u64 v[20:21], v[14:15], 0, s[4:5]
	global_load_dword v74, v[20:21], off
	v_lshl_add_u64 v[20:21], v[12:13], 0, s[4:5]
	s_add_u32 s4, s4, 0x8000
	s_addc_u32 s5, s5, 0
	s_cmp_lg_u32 s4, 0x40000
	global_load_dword v75, v[20:21], off
	v_lshl_add_u64 v[20:21], v[18:19], 0, s[4:5]
	global_load_dword v76, v[20:21], off
	v_lshl_add_u64 v[20:21], v[16:17], 0, s[4:5]
	global_load_dword v77, v[20:21], off
	v_lshl_add_u64 v[20:21], v[14:15], 0, s[4:5]
	global_load_dword v78, v[20:21], off
	v_lshl_add_u64 v[20:21], v[12:13], 0, s[4:5]
	s_add_u32 s4, s4, 0x8000
	s_addc_u32 s5, s5, 0
	s_cmp_lg_u32 s4, 0x40000
	global_load_dword v79, v[20:21], off
	s_waitcnt vmcnt(0)
	ds_write_b32 v6, v48
	ds_write_b32 v6, v49 offset:264
	ds_write_b32 v6, v50 offset:528
	ds_write_b32 v6, v51 offset:792
	ds_write_b32 v6, v52 offset:1056
	ds_write_b32 v6, v53 offset:1320
	ds_write_b32 v6, v54 offset:1584
	ds_write_b32 v6, v55 offset:1848
	ds_write_b32 v6, v56 offset:2112
	ds_write_b32 v6, v57 offset:2376
	ds_write_b32 v6, v58 offset:2640
	ds_write_b32 v6, v59 offset:2904
	ds_write_b32 v6, v60 offset:3168
	ds_write_b32 v6, v61 offset:3432
	ds_write_b32 v6, v62 offset:3696
	ds_write_b32 v6, v63 offset:3960
	ds_write_b32 v6, v64 offset:4224
	ds_write_b32 v6, v65 offset:4488
	ds_write_b32 v6, v66 offset:4752
	ds_write_b32 v6, v67 offset:5016
	ds_write_b32 v6, v68 offset:5280
	ds_write_b32 v6, v69 offset:5544
	ds_write_b32 v6, v70 offset:5808
	ds_write_b32 v6, v71 offset:6072
	ds_write_b32 v6, v72 offset:6336
	ds_write_b32 v6, v73 offset:6600
	ds_write_b32 v6, v74 offset:6864
	ds_write_b32 v6, v75 offset:7128
	ds_write_b32 v6, v76 offset:7392
	ds_write_b32 v6, v77 offset:7656
	ds_write_b32 v6, v78 offset:7920
	ds_write_b32 v6, v79 offset:8184
	v_add_u32_e32 v6, 0x2100, v6
	s_cbranch_scc1 .LBB0_34
; __device__ __forceinline__ unsigned cvt_pk_bf16(float lo, float hi) { unsigned r; asm volatile("v_cvt_pk_bf16_f32 %0, %1, %2" : "=v"(r) : "v"(lo), "v"(hi)); return r; }
; #define LAS __attribute__((address_space(3)))
; #define LDS_WAIT() asm volatile("s_waitcnt lgkmcnt(0)" ::: "memory")
; __device__ __forceinline__ void tr_item(KArg ka, int mat, int l, int K, bf16_t* WT, LAS float* scr, int kb, int nb, int lane) {
;     ...
;     const int c = lane & 7;
; #pragma unroll
;     for (int j = 0; j < 4; ++j) { const int n = (lane >> 3) + 8 * j; const LAS float* s = scr + (8 * c) * 33 + n;
;         u32x4 o; o.x = cvt_pk_bf16(s[0 * 33], s[1 * 33]); o.y = cvt_pk_bf16(s[2 * 33], s[3 * 33]); o.z = cvt_pk_bf16(s[4 * 33], s[5 * 33]); o.w = cvt_pk_bf16(s[6 * 33], s[7 * 33]);
;         *(u32x4*)(WT + (size_t)(n0 + n) * K + k0 + 8 * c) = o; }
;     LDS_WAIT(); asm volatile("" ::: "memory");
	s_and_b32 s4, 0xffff, s38
	s_waitcnt lgkmcnt(0)
	s_lshl_b32 s4, s4, 1
	s_add_u32 s4, s67, s4
	ds_read2_b32 v[12:13], v25 offset1:33
	v_mov_b32_e32 v11, v7
	v_add_u32_e32 v16, s12, v24
	s_addc_u32 s5, s66, 0
	s_waitcnt lgkmcnt(0)
	v_cvt_pk_bf16_f32 v12, v12, v13
	ds_read2_b32 v[14:15], v25 offset0:66 offset1:99
	v_ashrrev_i32_e32 v17, 31, v16
	v_lshl_add_u64 v[20:21], s[4:5], 0, v[10:11]
	s_waitcnt lgkmcnt(0)
	v_cvt_pk_bf16_f32 v13, v14, v15
	ds_read2_b32 v[14:15], v25 offset0:132 offset1:165
	v_lshlrev_b64 v[16:17], 10, v[16:17]
	v_lshl_add_u64 v[20:21], v[20:21], 0, s[22:23]
	s_waitcnt lgkmcnt(0)
	v_cvt_pk_bf16_f32 v14, v14, v15
	ds_read2_b32 v[18:19], v25 offset0:198 offset1:231
	v_lshl_add_u64 v[16:17], v[20:21], 0, v[16:17]
	s_waitcnt lgkmcnt(0)
	v_cvt_pk_bf16_f32 v15, v18, v19
	flat_store_dwordx4 v[16:17], v[12:15]
	v_add_u32_e32 v18, s12, v26
	ds_read2_b32 v[12:13], v25 offset0:8 offset1:41
	v_ashrrev_i32_e32 v19, 31, v18
	s_waitcnt lgkmcnt(0)
	v_cvt_pk_bf16_f32 v12, v12, v13
	ds_read2_b32 v[14:15], v25 offset0:74 offset1:107
	v_lshlrev_b64 v[18:19], 10, v[18:19]
	s_waitcnt lgkmcnt(0)
	v_cvt_pk_bf16_f32 v13, v14, v15
	ds_read2_b32 v[14:15], v25 offset0:140 offset1:173
	v_lshl_add_u64 v[18:19], v[20:21], 0, v[18:19]
	s_waitcnt lgkmcnt(0)
	v_cvt_pk_bf16_f32 v14, v14, v15
	ds_read2_b32 v[16:17], v25 offset0:206 offset1:239
	s_waitcnt lgkmcnt(0)
	v_cvt_pk_bf16_f32 v15, v16, v17
	flat_store_dwordx4 v[18:19], v[12:15]
	v_add_u32_e32 v18, s12, v27
	ds_read2_b32 v[12:13], v25 offset0:16 offset1:49
	v_ashrrev_i32_e32 v19, 31, v18
	s_waitcnt lgkmcnt(0)
	v_cvt_pk_bf16_f32 v12, v12, v13
	ds_read2_b32 v[14:15], v25 offset0:82 offset1:115
	v_lshlrev_b64 v[18:19], 10, v[18:19]
	s_waitcnt lgkmcnt(0)
	v_cvt_pk_bf16_f32 v13, v14, v15
	ds_read2_b32 v[14:15], v25 offset0:148 offset1:181
	v_lshl_add_u64 v[18:19], v[20:21], 0, v[18:19]
	s_waitcnt lgkmcnt(0)
	v_cvt_pk_bf16_f32 v14, v14, v15
	ds_read2_b32 v[16:17], v25 offset0:214 offset1:247
	s_waitcnt lgkmcnt(0)
	v_cvt_pk_bf16_f32 v15, v16, v17
	flat_store_dwordx4 v[18:19], v[12:15]
	ds_read2_b32 v[12:13], v25 offset0:24 offset1:57
	v_add_u32_e32 v18, s12, v28
	s_waitcnt lgkmcnt(0)
	v_cvt_pk_bf16_f32 v12, v12, v13
	ds_read2_b32 v[14:15], v25 offset0:90 offset1:123
	s_waitcnt lgkmcnt(0)
	v_cvt_pk_bf16_f32 v13, v14, v15
	ds_read2_b32 v[14:15], v25 offset0:156 offset1:189
	v_ashrrev_i32_e32 v19, 31, v18
	s_waitcnt lgkmcnt(0)
	v_cvt_pk_bf16_f32 v14, v14, v15
	ds_read2_b32 v[16:17], v25 offset0:222 offset1:255
	v_lshlrev_b64 v[18:19], 10, v[18:19]
	s_waitcnt lgkmcnt(0)
	v_cvt_pk_bf16_f32 v15, v16, v17
	v_lshl_add_u64 v[16:17], v[20:21], 0, v[18:19]
	flat_store_dwordx4 v[16:17], v[12:15]
	s_waitcnt lgkmcnt(0)

; __device__ __forceinline__ float wval(KArg ka, int mat, int l, int k, int n) {
;     ...
;     case M_UQ: { const int h = n / 96, j = n % 96; const int src = j < 64 ? h * 96 + j : h * 96 + 64 + ((j - 64) >> 1) + 16 * ((j - 64) & 1);
;                  return PIN(I_WUQ)[((size_t)l * QL + k) * QW + src] * PIN(I_QN)[l * QL + k] * 0.14724445f; }
; __device__ __forceinline__ void tr_item(KArg ka, int mat, int l, int K, bf16_t* WT, LAS float* scr, int kb, int nb, int lane) {
;     const int k0 = 64 * kb, n0 = 32 * nb;
; #pragma unroll 4
;     for (int i = 0; i < 32; ++i) { const int kk = 2 * i + (lane >> 5); scr[kk * 33 + (lane & 31)] = wval(ka, mat, l, k0 + kk, n0 + (lane & 31)); }
.LBB0_73:
	v_lshl_add_u64 v[40:41], v[22:23], 0, s[4:5]
	global_load_dword v48, v[20:21], off
	global_load_dword v49, v[40:41], off
	v_lshl_add_u64 v[40:41], v[16:17], 0, s[4:5]
	v_add_co_u32_e32 v42, vcc, -16, v18
	v_lshl_add_u64 v[20:21], v[20:21], 0, 32
	s_nop 0
	v_addc_co_u32_e32 v43, vcc, -1, v19, vcc
	global_load_dword v50, v[40:41], off
	global_load_dword v51, v[42:43], off
	v_lshl_add_u64 v[40:41], v[14:15], 0, s[4:5]
	v_add_co_u32_e32 v42, vcc, -8, v18
	v_addc_co_u32_e32 v43, vcc, -1, v19, vcc
	global_load_dword v52, v[40:41], off
	s_nop 0
	global_load_dword v53, v[42:43], off
	v_lshl_add_u64 v[40:41], v[12:13], 0, s[4:5]
	s_add_u32 s4, s4, 0x6000
	s_addc_u32 s5, s5, 0
	s_cmp_lg_u32 s4, 0x30000
	global_load_dword v54, v[40:41], off
	s_nop 0
	global_load_dword v55, v[18:19], off
	v_lshl_add_u64 v[18:19], v[18:19], 0, 32
	v_lshl_add_u64 v[40:41], v[22:23], 0, s[4:5]
	global_load_dword v56, v[20:21], off
	global_load_dword v57, v[40:41], off
	v_lshl_add_u64 v[40:41], v[16:17], 0, s[4:5]
	v_add_co_u32_e32 v42, vcc, -16, v18
	v_lshl_add_u64 v[20:21], v[20:21], 0, 32
	s_nop 0
	v_addc_co_u32_e32 v43, vcc, -1, v19, vcc
	global_load_dword v58, v[40:41], off
	global_load_dword v59, v[42:43], off
	v_lshl_add_u64 v[40:41], v[14:15], 0, s[4:5]
	v_add_co_u32_e32 v42, vcc, -8, v18
	v_addc_co_u32_e32 v43, vcc, -1, v19, vcc
	global_load_dword v60, v[40:41], off
	s_nop 0
	global_load_dword v61, v[42:43], off
	v_lshl_add_u64 v[40:41], v[12:13], 0, s[4:5]
	s_add_u32 s4, s4, 0x6000
	s_addc_u32 s5, s5, 0
	s_cmp_lg_u32 s4, 0x30000
	global_load_dword v62, v[40:41], off
	s_nop 0
	global_load_dword v63, v[18:19], off
	v_lshl_add_u64 v[18:19], v[18:19], 0, 32
	v_lshl_add_u64 v[40:41], v[22:23], 0, s[4:5]
	global_load_dword v64, v[20:21], off
	global_load_dword v65, v[40:41], off
	v_lshl_add_u64 v[40:41], v[16:17], 0, s[4:5]
	v_add_co_u32_e32 v42, vcc, -16, v18
	v_lshl_add_u64 v[20:21], v[20:21], 0, 32
	s_nop 0
	v_addc_co_u32_e32 v43, vcc, -1, v19, vcc
	global_load_dword v66, v[40:41], off
	global_load_dword v67, v[42:43], off
	v_lshl_add_u64 v[40:41], v[14:15], 0, s[4:5]
	v_add_co_u32_e32 v42, vcc, -8, v18
	v_addc_co_u32_e32 v43, vcc, -1, v19, vcc
	global_load_dword v68, v[40:41], off
	s_nop 0
	global_load_dword v69, v[42:43], off
	v_lshl_add_u64 v[40:41], v[12:13], 0, s[4:5]
	s_add_u32 s4, s4, 0x6000
	s_addc_u32 s5, s5, 0
	s_cmp_lg_u32 s4, 0x30000
	global_load_dword v70, v[40:41], off
	s_nop 0
	global_load_dword v71, v[18:19], off
	v_lshl_add_u64 v[18:19], v[18:19], 0, 32
	v_lshl_add_u64 v[40:41], v[22:23], 0, s[4:5]
	global_load_dword v72, v[20:21], off
	global_load_dword v73, v[40:41], off
	v_lshl_add_u64 v[40:41], v[16:17], 0, s[4:5]
	v_add_co_u32_e32 v42, vcc, -16, v18
	v_lshl_add_u64 v[20:21], v[20:21], 0, 32
	s_nop 0
	v_addc_co_u32_e32 v43, vcc, -1, v19, vcc
	global_load_dword v74, v[40:41], off
	global_load_dword v75, v[42:43], off
	v_lshl_add_u64 v[40:41], v[14:15], 0, s[4:5]
	v_add_co_u32_e32 v42, vcc, -8, v18
	v_addc_co_u32_e32 v43, vcc, -1, v19, vcc
	global_load_dword v76, v[40:41], off
	s_nop 0
	global_load_dword v77, v[42:43], off
	v_lshl_add_u64 v[40:41], v[12:13], 0, s[4:5]
	s_add_u32 s4, s4, 0x6000
	s_addc_u32 s5, s5, 0
	s_cmp_lg_u32 s4, 0x30000
	global_load_dword v78, v[40:41], off
	s_nop 0
	global_load_dword v79, v[18:19], off
	v_lshl_add_u64 v[18:19], v[18:19], 0, 32
	v_lshl_add_u64 v[40:41], v[22:23], 0, s[4:5]
	global_load_dword v80, v[20:21], off
	global_load_dword v81, v[40:41], off
	v_lshl_add_u64 v[40:41], v[16:17], 0, s[4:5]
	v_add_co_u32_e32 v42, vcc, -16, v18
	v_lshl_add_u64 v[20:21], v[20:21], 0, 32
	s_nop 0
	v_addc_co_u32_e32 v43, vcc, -1, v19, vcc
	global_load_dword v82, v[40:41], off
	global_load_dword v83, v[42:43], off
	v_lshl_add_u64 v[40:41], v[14:15], 0, s[4:5]
	v_add_co_u32_e32 v42, vcc, -8, v18
	v_addc_co_u32_e32 v43, vcc, -1, v19, vcc
	global_load_dword v84, v[40:41], off
	s_nop 0
	global_load_dword v85, v[42:43], off
	v_lshl_add_u64 v[40:41], v[12:13], 0, s[4:5]
	s_add_u32 s4, s4, 0x6000
	s_addc_u32 s5, s5, 0
	s_cmp_lg_u32 s4, 0x30000
	global_load_dword v86, v[40:41], off
	s_nop 0
	global_load_dword v87, v[18:19], off
	v_lshl_add_u64 v[18:19], v[18:19], 0, 32
	v_lshl_add_u64 v[40:41], v[22:23], 0, s[4:5]
	global_load_dword v88, v[20:21], off
	global_load_dword v89, v[40:41], off
	v_lshl_add_u64 v[40:41], v[16:17], 0, s[4:5]
	v_add_co_u32_e32 v42, vcc, -16, v18
	v_lshl_add_u64 v[20:21], v[20:21], 0, 32
	s_nop 0
	v_addc_co_u32_e32 v43, vcc, -1, v19, vcc
	global_load_dword v90, v[40:41], off
	global_load_dword v91, v[42:43], off
	v_lshl_add_u64 v[40:41], v[14:15], 0, s[4:5]
	v_add_co_u32_e32 v42, vcc, -8, v18
	v_addc_co_u32_e32 v43, vcc, -1, v19, vcc
	global_load_dword v92, v[40:41], off
	s_nop 0
	global_load_dword v93, v[42:43], off
	v_lshl_add_u64 v[40:41], v[12:13], 0, s[4:5]
	s_add_u32 s4, s4, 0x6000
	s_addc_u32 s5, s5, 0
	s_cmp_lg_u32 s4, 0x30000
	global_load_dword v94, v[40:41], off
	s_nop 0
	global_load_dword v95, v[18:19], off
	v_lshl_add_u64 v[18:19], v[18:19], 0, 32
	v_lshl_add_u64 v[40:41], v[22:23], 0, s[4:5]
	global_load_dword v96, v[20:21], off
	global_load_dword v97, v[40:41], off
	v_lshl_add_u64 v[40:41], v[16:17], 0, s[4:5]
	v_add_co_u32_e32 v42, vcc, -16, v18
	v_lshl_add_u64 v[20:21], v[20:21], 0, 32
	s_nop 0
	v_addc_co_u32_e32 v43, vcc, -1, v19, vcc
	global_load_dword v98, v[40:41], off
	global_load_dword v99, v[42:43], off
	v_lshl_add_u64 v[40:41], v[14:15], 0, s[4:5]
	v_add_co_u32_e32 v42, vcc, -8, v18
	v_addc_co_u32_e32 v43, vcc, -1, v19, vcc
	global_load_dword v100, v[40:41], off
	s_nop 0
	global_load_dword v101, v[42:43], off
	v_lshl_add_u64 v[40:41], v[12:13], 0, s[4:5]
	s_add_u32 s4, s4, 0x6000
	s_addc_u32 s5, s5, 0
	s_cmp_lg_u32 s4, 0x30000
	global_load_dword v102, v[40:41], off
	s_nop 0
	global_load_dword v103, v[18:19], off
	v_lshl_add_u64 v[18:19], v[18:19], 0, 32
	v_lshl_add_u64 v[40:41], v[22:23], 0, s[4:5]
	global_load_dword v104, v[20:21], off
	global_load_dword v105, v[40:41], off
	v_lshl_add_u64 v[40:41], v[16:17], 0, s[4:5]
	v_add_co_u32_e32 v42, vcc, -16, v18
	v_lshl_add_u64 v[20:21], v[20:21], 0, 32
	s_nop 0
	v_addc_co_u32_e32 v43, vcc, -1, v19, vcc
	global_load_dword v106, v[40:41], off
	global_load_dword v107, v[42:43], off
	v_lshl_add_u64 v[40:41], v[14:15], 0, s[4:5]
	v_add_co_u32_e32 v42, vcc, -8, v18
	v_addc_co_u32_e32 v43, vcc, -1, v19, vcc
	global_load_dword v108, v[40:41], off
	s_nop 0
	global_load_dword v109, v[42:43], off
	v_lshl_add_u64 v[40:41], v[12:13], 0, s[4:5]
	s_add_u32 s4, s4, 0x6000
	s_addc_u32 s5, s5, 0
	s_cmp_lg_u32 s4, 0x30000
	global_load_dword v110, v[40:41], off
	s_nop 0
	global_load_dword v111, v[18:19], off
	v_lshl_add_u64 v[18:19], v[18:19], 0, 32
	s_waitcnt vmcnt(0)
; __device__ __forceinline__ unsigned cvt_pk_bf16(float lo, float hi) { unsigned r; asm volatile("v_cvt_pk_bf16_f32 %0, %1, %2" : "=v"(r) : "v"(lo), "v"(hi)); return r; }
; #define LAS __attribute__((address_space(3)))
; #define LDS_WAIT() asm volatile("s_waitcnt lgkmcnt(0)" ::: "memory")
; __device__ __forceinline__ float wval(KArg ka, int mat, int l, int k, int n) {
;     ...
;     case M_UQ: { const int h = n / 96, j = n % 96; const int src = j < 64 ? h * 96 + j : h * 96 + 64 + ((j - 64) >> 1) + 16 * ((j - 64) & 1);
;                  return PIN(I_WUQ)[((size_t)l * QL + k) * QW + src] * PIN(I_QN)[l * QL + k] * 0.14724445f; }
; __device__ __forceinline__ void tr_item(KArg ka, int mat, int l, int K, bf16_t* WT, LAS float* scr, int kb, int nb, int lane) {
;     ...
;     for (int i = 0; i < 32; ++i) { const int kk = 2 * i + (lane >> 5); scr[kk * 33 + (lane & 31)] = wval(ka, mat, l, k0 + kk, n0 + (lane & 31)); }
;     LDS_WAIT(); asm volatile("" ::: "memory");
;     const int c = lane & 7;
; #pragma unroll
;     for (int j = 0; j < 4; ++j) { const int n = (lane >> 3) + 8 * j; const LAS float* s = scr + (8 * c) * 33 + n;
;         u32x4 o; o.x = cvt_pk_bf16(s[0 * 33], s[1 * 33]); o.y = cvt_pk_bf16(s[2 * 33], s[3 * 33]); o.z = cvt_pk_bf16(s[4 * 33], s[5 * 33]); o.w = cvt_pk_bf16(s[6 * 33], s[7 * 33]);
;         *(u32x4*)(WT + (size_t)(n0 + n) * K + k0 + 8 * c) = o; }
;     LDS_WAIT(); asm volatile("" ::: "memory");
	v_mul_f32_e32 v48, v49, v48
	v_mul_f32_e32 v48, 0x3e16c740, v48
	ds_write_b32 v6, v48
	v_mul_f32_e32 v51, v50, v51
	v_mul_f32_e32 v51, 0x3e16c740, v51
	ds_write_b32 v6, v51 offset:264
	v_mul_f32_e32 v53, v52, v53
	v_mul_f32_e32 v53, 0x3e16c740, v53
	ds_write_b32 v6, v53 offset:528
	v_mul_f32_e32 v55, v54, v55
	v_mul_f32_e32 v55, 0x3e16c740, v55
	ds_write_b32 v6, v55 offset:792
	v_mul_f32_e32 v56, v57, v56
	v_mul_f32_e32 v56, 0x3e16c740, v56
	ds_write_b32 v6, v56 offset:1056
	v_mul_f32_e32 v59, v58, v59
	v_mul_f32_e32 v59, 0x3e16c740, v59
	ds_write_b32 v6, v59 offset:1320
	v_mul_f32_e32 v61, v60, v61
	v_mul_f32_e32 v61, 0x3e16c740, v61
	ds_write_b32 v6, v61 offset:1584
	v_mul_f32_e32 v63, v62, v63
	v_mul_f32_e32 v63, 0x3e16c740, v63
	ds_write_b32 v6, v63 offset:1848
	v_mul_f32_e32 v64, v65, v64
	v_mul_f32_e32 v64, 0x3e16c740, v64
	ds_write_b32 v6, v64 offset:2112
	v_mul_f32_e32 v67, v66, v67
	v_mul_f32_e32 v67, 0x3e16c740, v67
	ds_write_b32 v6, v67 offset:2376
	v_mul_f32_e32 v69, v68, v69
	v_mul_f32_e32 v69, 0x3e16c740, v69
	ds_write_b32 v6, v69 offset:2640
	v_mul_f32_e32 v71, v70, v71
	v_mul_f32_e32 v71, 0x3e16c740, v71
	ds_write_b32 v6, v71 offset:2904
	v_mul_f32_e32 v72, v73, v72
	v_mul_f32_e32 v72, 0x3e16c740, v72
	ds_write_b32 v6, v72 offset:3168
	v_mul_f32_e32 v75, v74, v75
	v_mul_f32_e32 v75, 0x3e16c740, v75
	ds_write_b32 v6, v75 offset:3432
	v_mul_f32_e32 v77, v76, v77
	v_mul_f32_e32 v77, 0x3e16c740, v77
	ds_write_b32 v6, v77 offset:3696
	v_mul_f32_e32 v79, v78, v79
	v_mul_f32_e32 v79, 0x3e16c740, v79
	ds_write_b32 v6, v79 offset:3960
	v_mul_f32_e32 v80, v81, v80
	v_mul_f32_e32 v80, 0x3e16c740, v80
	ds_write_b32 v6, v80 offset:4224
	v_mul_f32_e32 v83, v82, v83
	v_mul_f32_e32 v83, 0x3e16c740, v83
	ds_write_b32 v6, v83 offset:4488
	v_mul_f32_e32 v85, v84, v85
	v_mul_f32_e32 v85, 0x3e16c740, v85
	ds_write_b32 v6, v85 offset:4752
	v_mul_f32_e32 v87, v86, v87
	v_mul_f32_e32 v87, 0x3e16c740, v87
	ds_write_b32 v6, v87 offset:5016
	v_mul_f32_e32 v88, v89, v88
	v_mul_f32_e32 v88, 0x3e16c740, v88
	ds_write_b32 v6, v88 offset:5280
	v_mul_f32_e32 v91, v90, v91
	v_mul_f32_e32 v91, 0x3e16c740, v91
	ds_write_b32 v6, v91 offset:5544
	v_mul_f32_e32 v93, v92, v93
	v_mul_f32_e32 v93, 0x3e16c740, v93
	ds_write_b32 v6, v93 offset:5808
	v_mul_f32_e32 v95, v94, v95
	v_mul_f32_e32 v95, 0x3e16c740, v95
	ds_write_b32 v6, v95 offset:6072
	v_mul_f32_e32 v96, v97, v96
	v_mul_f32_e32 v96, 0x3e16c740, v96
	ds_write_b32 v6, v96 offset:6336
	v_mul_f32_e32 v99, v98, v99
	v_mul_f32_e32 v99, 0x3e16c740, v99
	ds_write_b32 v6, v99 offset:6600
	v_mul_f32_e32 v101, v100, v101
	v_mul_f32_e32 v101, 0x3e16c740, v101
	ds_write_b32 v6, v101 offset:6864
	v_mul_f32_e32 v103, v102, v103
	v_mul_f32_e32 v103, 0x3e16c740, v103
	ds_write_b32 v6, v103 offset:7128
	v_mul_f32_e32 v104, v105, v104
	v_mul_f32_e32 v104, 0x3e16c740, v104
	ds_write_b32 v6, v104 offset:7392
	v_mul_f32_e32 v107, v106, v107
	v_mul_f32_e32 v107, 0x3e16c740, v107
	ds_write_b32 v6, v107 offset:7656
	v_mul_f32_e32 v109, v108, v109
	v_mul_f32_e32 v109, 0x3e16c740, v109
	ds_write_b32 v6, v109 offset:7920
	v_mul_f32_e32 v111, v110, v111
	v_mul_f32_e32 v111, 0x3e16c740, v111
	ds_write_b32 v6, v111 offset:8184
	v_add_u32_e32 v6, 0x2100, v6
	s_cbranch_scc1 .LBB0_73
	s_lshl_b32 s4, s37, 1
	s_waitcnt lgkmcnt(0)
	s_add_u32 s4, s67, s4
	v_mov_b32_e32 v11, v7
	s_addc_u32 s5, s66, 0
	ds_read2_b32 v[12:13], v25 offset1:33
	v_lshl_add_u64 v[18:19], s[4:5], 0, v[10:11]
	s_waitcnt lgkmcnt(0)
	v_cvt_pk_bf16_f32 v12, v12, v13
	ds_read2_b32 v[14:15], v25 offset0:66 offset1:99
	v_add_u32_e32 v6, s12, v24
	v_lshl_add_u64 v[18:19], v[18:19], 0, s[30:31]
	s_waitcnt lgkmcnt(0)
	v_cvt_pk_bf16_f32 v13, v14, v15
	ds_read2_b32 v[14:15], v25 offset0:132 offset1:165
	v_mad_i64_i32 v[20:21], s[4:5], v6, s60, v[18:19]
	s_waitcnt lgkmcnt(0)
	v_cvt_pk_bf16_f32 v14, v14, v15
	ds_read2_b32 v[16:17], v25 offset0:198 offset1:231
	s_waitcnt lgkmcnt(0)
	v_cvt_pk_bf16_f32 v15, v16, v17
	flat_store_dwordx4 v[20:21], v[12:15]
	ds_read2_b32 v[12:13], v25 offset0:8 offset1:41
	v_add_u32_e32 v6, s12, v26
	s_waitcnt lgkmcnt(0)
	v_cvt_pk_bf16_f32 v12, v12, v13
	ds_read2_b32 v[14:15], v25 offset0:74 offset1:107
	s_waitcnt lgkmcnt(0)
	v_cvt_pk_bf16_f32 v13, v14, v15
	ds_read2_b32 v[14:15], v25 offset0:140 offset1:173
	v_mad_i64_i32 v[20:21], s[4:5], v6, s60, v[18:19]
	s_waitcnt lgkmcnt(0)
	v_cvt_pk_bf16_f32 v14, v14, v15
	ds_read2_b32 v[16:17], v25 offset0:206 offset1:239
	s_waitcnt lgkmcnt(0)
	v_cvt_pk_bf16_f32 v15, v16, v17
	flat_store_dwordx4 v[20:21], v[12:15]
	ds_read2_b32 v[12:13], v25 offset0:16 offset1:49
	v_add_u32_e32 v6, s12, v27
	s_waitcnt lgkmcnt(0)
	v_cvt_pk_bf16_f32 v12, v12, v13
	ds_read2_b32 v[14:15], v25 offset0:82 offset1:115
	s_waitcnt lgkmcnt(0)
	v_cvt_pk_bf16_f32 v13, v14, v15
	ds_read2_b32 v[14:15], v25 offset0:148 offset1:181
	v_mad_i64_i32 v[20:21], s[4:5], v6, s60, v[18:19]
	s_waitcnt lgkmcnt(0)
	v_cvt_pk_bf16_f32 v14, v14, v15
	ds_read2_b32 v[16:17], v25 offset0:214 offset1:247
	s_waitcnt lgkmcnt(0)
	v_cvt_pk_bf16_f32 v15, v16, v17
	flat_store_dwordx4 v[20:21], v[12:15]
	ds_read2_b32 v[12:13], v25 offset0:24 offset1:57
	v_add_u32_e32 v6, s12, v28
	s_waitcnt lgkmcnt(0)
	v_cvt_pk_bf16_f32 v12, v12, v13
	ds_read2_b32 v[14:15], v25 offset0:90 offset1:123
	s_waitcnt lgkmcnt(0)
	v_cvt_pk_bf16_f32 v13, v14, v15
	ds_read2_b32 v[14:15], v25 offset0:156 offset1:189
	s_waitcnt lgkmcnt(0)
	v_cvt_pk_bf16_f32 v14, v14, v15
	ds_read2_b32 v[16:17], v25 offset0:222 offset1:255
	s_waitcnt lgkmcnt(0)
	v_cvt_pk_bf16_f32 v15, v16, v17
	v_mad_i64_i32 v[16:17], s[4:5], v6, s60, v[18:19]
	flat_store_dwordx4 v[16:17], v[12:15]
	s_waitcnt lgkmcnt(0)

; __device__ __forceinline__ float wval(KArg ka, int mat, int l, int k, int n) {
;     ...
;     case M_GATE: return PIN(I_WGATE)[((size_t)l * 1024 + k) * 3072 + n] * PIN(I_LMPRE)[l * 1024 + k];
; __device__ __forceinline__ void tr_item(KArg ka, int mat, int l, int K, bf16_t* WT, LAS float* scr, int kb, int nb, int lane) {
;     const int k0 = 64 * kb, n0 = 32 * nb;
; #pragma unroll 4
;     for (int i = 0; i < 32; ++i) { const int kk = 2 * i + (lane >> 5); scr[kk * 33 + (lane & 31)] = wval(ka, mat, l, k0 + kk, n0 + (lane & 31)); }
.LBB0_78:
	v_lshl_add_u64 v[40:41], v[22:23], 0, s[4:5]
	global_load_dword v48, v[20:21], off
	global_load_dword v49, v[40:41], off
	v_lshl_add_u64 v[40:41], v[16:17], 0, s[4:5]
	v_add_co_u32_e32 v42, vcc, -16, v18
	v_lshl_add_u64 v[20:21], v[20:21], 0, 32
	s_nop 0
	v_addc_co_u32_e32 v43, vcc, -1, v19, vcc
	global_load_dword v50, v[40:41], off
	global_load_dword v51, v[42:43], off
	v_lshl_add_u64 v[40:41], v[14:15], 0, s[4:5]
	v_add_co_u32_e32 v42, vcc, -8, v18
	v_addc_co_u32_e32 v43, vcc, -1, v19, vcc
	global_load_dword v52, v[40:41], off
	s_nop 0
	global_load_dword v53, v[42:43], off
	v_lshl_add_u64 v[40:41], v[12:13], 0, s[4:5]
	s_add_u32 s4, s4, 0x18000
	s_addc_u32 s5, s5, 0
	s_cmp_lg_u32 s4, 0xc0000
	global_load_dword v54, v[40:41], off
	s_nop 0
	global_load_dword v55, v[18:19], off
	v_lshl_add_u64 v[18:19], v[18:19], 0, 32
	v_lshl_add_u64 v[40:41], v[22:23], 0, s[4:5]
	global_load_dword v56, v[20:21], off
	global_load_dword v57, v[40:41], off
	v_lshl_add_u64 v[40:41], v[16:17], 0, s[4:5]
	v_add_co_u32_e32 v42, vcc, -16, v18
	v_lshl_add_u64 v[20:21], v[20:21], 0, 32
	s_nop 0
	v_addc_co_u32_e32 v43, vcc, -1, v19, vcc
	global_load_dword v58, v[40:41], off
	global_load_dword v59, v[42:43], off
	v_lshl_add_u64 v[40:41], v[14:15], 0, s[4:5]
	v_add_co_u32_e32 v42, vcc, -8, v18
	v_addc_co_u32_e32 v43, vcc, -1, v19, vcc
	global_load_dword v60, v[40:41], off
	s_nop 0
	global_load_dword v61, v[42:43], off
	v_lshl_add_u64 v[40:41], v[12:13], 0, s[4:5]
	s_add_u32 s4, s4, 0x18000
	s_addc_u32 s5, s5, 0
	s_cmp_lg_u32 s4, 0xc0000
	global_load_dword v62, v[40:41], off
	s_nop 0
	global_load_dword v63, v[18:19], off
	v_lshl_add_u64 v[18:19], v[18:19], 0, 32
	v_lshl_add_u64 v[40:41], v[22:23], 0, s[4:5]
	global_load_dword v64, v[20:21], off
	global_load_dword v65, v[40:41], off
	v_lshl_add_u64 v[40:41], v[16:17], 0, s[4:5]
	v_add_co_u32_e32 v42, vcc, -16, v18
	v_lshl_add_u64 v[20:21], v[20:21], 0, 32
	s_nop 0
	v_addc_co_u32_e32 v43, vcc, -1, v19, vcc
	global_load_dword v66, v[40:41], off
	global_load_dword v67, v[42:43], off
	v_lshl_add_u64 v[40:41], v[14:15], 0, s[4:5]
	v_add_co_u32_e32 v42, vcc, -8, v18
	v_addc_co_u32_e32 v43, vcc, -1, v19, vcc
	global_load_dword v68, v[40:41], off
	s_nop 0
	global_load_dword v69, v[42:43], off
	v_lshl_add_u64 v[40:41], v[12:13], 0, s[4:5]
	s_add_u32 s4, s4, 0x18000
	s_addc_u32 s5, s5, 0
	s_cmp_lg_u32 s4, 0xc0000
	global_load_dword v70, v[40:41], off
	s_nop 0
	global_load_dword v71, v[18:19], off
	v_lshl_add_u64 v[18:19], v[18:19], 0, 32
	v_lshl_add_u64 v[40:41], v[22:23], 0, s[4:5]
	global_load_dword v72, v[20:21], off
	global_load_dword v73, v[40:41], off
	v_lshl_add_u64 v[40:41], v[16:17], 0, s[4:5]
	v_add_co_u32_e32 v42, vcc, -16, v18
	v_lshl_add_u64 v[20:21], v[20:21], 0, 32
	s_nop 0
	v_addc_co_u32_e32 v43, vcc, -1, v19, vcc
	global_load_dword v74, v[40:41], off
	global_load_dword v75, v[42:43], off
	v_lshl_add_u64 v[40:41], v[14:15], 0, s[4:5]
	v_add_co_u32_e32 v42, vcc, -8, v18
	v_addc_co_u32_e32 v43, vcc, -1, v19, vcc
	global_load_dword v76, v[40:41], off
	s_nop 0
	global_load_dword v77, v[42:43], off
	v_lshl_add_u64 v[40:41], v[12:13], 0, s[4:5]
	s_add_u32 s4, s4, 0x18000
	s_addc_u32 s5, s5, 0
	s_cmp_lg_u32 s4, 0xc0000
	global_load_dword v78, v[40:41], off
	s_nop 0
	global_load_dword v79, v[18:19], off
	v_lshl_add_u64 v[18:19], v[18:19], 0, 32
	v_lshl_add_u64 v[40:41], v[22:23], 0, s[4:5]
	global_load_dword v80, v[20:21], off
	global_load_dword v81, v[40:41], off
	v_lshl_add_u64 v[40:41], v[16:17], 0, s[4:5]
	v_add_co_u32_e32 v42, vcc, -16, v18
	v_lshl_add_u64 v[20:21], v[20:21], 0, 32
	s_nop 0
	v_addc_co_u32_e32 v43, vcc, -1, v19, vcc
	global_load_dword v82, v[40:41], off
	global_load_dword v83, v[42:43], off
	v_lshl_add_u64 v[40:41], v[14:15], 0, s[4:5]
	v_add_co_u32_e32 v42, vcc, -8, v18
	v_addc_co_u32_e32 v43, vcc, -1, v19, vcc
	global_load_dword v84, v[40:41], off
	s_nop 0
	global_load_dword v85, v[42:43], off
	v_lshl_add_u64 v[40:41], v[12:13], 0, s[4:5]
	s_add_u32 s4, s4, 0x18000
	s_addc_u32 s5, s5, 0
	s_cmp_lg_u32 s4, 0xc0000
	global_load_dword v86, v[40:41], off
	s_nop 0
	global_load_dword v87, v[18:19], off
	v_lshl_add_u64 v[18:19], v[18:19], 0, 32
	v_lshl_add_u64 v[40:41], v[22:23], 0, s[4:5]
	global_load_dword v88, v[20:21], off
	global_load_dword v89, v[40:41], off
	v_lshl_add_u64 v[40:41], v[16:17], 0, s[4:5]
	v_add_co_u32_e32 v42, vcc, -16, v18
	v_lshl_add_u64 v[20:21], v[20:21], 0, 32
	s_nop 0
	v_addc_co_u32_e32 v43, vcc, -1, v19, vcc
	global_load_dword v90, v[40:41], off
	global_load_dword v91, v[42:43], off
	v_lshl_add_u64 v[40:41], v[14:15], 0, s[4:5]
	v_add_co_u32_e32 v42, vcc, -8, v18
	v_addc_co_u32_e32 v43, vcc, -1, v19, vcc
	global_load_dword v92, v[40:41], off
	s_nop 0
	global_load_dword v93, v[42:43], off
	v_lshl_add_u64 v[40:41], v[12:13], 0, s[4:5]
	s_add_u32 s4, s4, 0x18000
	s_addc_u32 s5, s5, 0
	s_cmp_lg_u32 s4, 0xc0000
	global_load_dword v94, v[40:41], off
	s_nop 0
	global_load_dword v95, v[18:19], off
	v_lshl_add_u64 v[18:19], v[18:19], 0, 32
	v_lshl_add_u64 v[40:41], v[22:23], 0, s[4:5]
	global_load_dword v96, v[20:21], off
	global_load_dword v97, v[40:41], off
	v_lshl_add_u64 v[40:41], v[16:17], 0, s[4:5]
	v_add_co_u32_e32 v42, vcc, -16, v18
	v_lshl_add_u64 v[20:21], v[20:21], 0, 32
	s_nop 0
	v_addc_co_u32_e32 v43, vcc, -1, v19, vcc
	global_load_dword v98, v[40:41], off
	global_load_dword v99, v[42:43], off
	v_lshl_add_u64 v[40:41], v[14:15], 0, s[4:5]
	v_add_co_u32_e32 v42, vcc, -8, v18
	v_addc_co_u32_e32 v43, vcc, -1, v19, vcc
	global_load_dword v100, v[40:41], off
	s_nop 0
	global_load_dword v101, v[42:43], off
	v_lshl_add_u64 v[40:41], v[12:13], 0, s[4:5]
	s_add_u32 s4, s4, 0x18000
	s_addc_u32 s5, s5, 0
	s_cmp_lg_u32 s4, 0xc0000
	global_load_dword v102, v[40:41], off
	s_nop 0
	global_load_dword v103, v[18:19], off
	v_lshl_add_u64 v[18:19], v[18:19], 0, 32
	v_lshl_add_u64 v[40:41], v[22:23], 0, s[4:5]
	global_load_dword v104, v[20:21], off
	global_load_dword v105, v[40:41], off
	v_lshl_add_u64 v[40:41], v[16:17], 0, s[4:5]
	v_add_co_u32_e32 v42, vcc, -16, v18
	v_lshl_add_u64 v[20:21], v[20:21], 0, 32
	s_nop 0
	v_addc_co_u32_e32 v43, vcc, -1, v19, vcc
	global_load_dword v106, v[40:41], off
	global_load_dword v107, v[42:43], off
	v_lshl_add_u64 v[40:41], v[14:15], 0, s[4:5]
	v_add_co_u32_e32 v42, vcc, -8, v18
	v_addc_co_u32_e32 v43, vcc, -1, v19, vcc
	global_load_dword v108, v[40:41], off
	s_nop 0
	global_load_dword v109, v[42:43], off
	v_lshl_add_u64 v[40:41], v[12:13], 0, s[4:5]
	s_add_u32 s4, s4, 0x18000
	s_addc_u32 s5, s5, 0
	s_cmp_lg_u32 s4, 0xc0000
	global_load_dword v110, v[40:41], off
	s_nop 0
	global_load_dword v111, v[18:19], off
	v_lshl_add_u64 v[18:19], v[18:19], 0, 32
	s_waitcnt vmcnt(0)
; __device__ __forceinline__ unsigned cvt_pk_bf16(float lo, float hi) { unsigned r; asm volatile("v_cvt_pk_bf16_f32 %0, %1, %2" : "=v"(r) : "v"(lo), "v"(hi)); return r; }
; #define LAS __attribute__((address_space(3)))
; #define LDS_WAIT() asm volatile("s_waitcnt lgkmcnt(0)" ::: "memory")
; __device__ __forceinline__ float wval(KArg ka, int mat, int l, int k, int n) {
;     ...
;     case M_GATE: return PIN(I_WGATE)[((size_t)l * 1024 + k) * 3072 + n] * PIN(I_LMPRE)[l * 1024 + k];
; __device__ __forceinline__ void tr_item(KArg ka, int mat, int l, int K, bf16_t* WT, LAS float* scr, int kb, int nb, int lane) {
;     ...
;     for (int i = 0; i < 32; ++i) { const int kk = 2 * i + (lane >> 5); scr[kk * 33 + (lane & 31)] = wval(ka, mat, l, k0 + kk, n0 + (lane & 31)); }
;     LDS_WAIT(); asm volatile("" ::: "memory");
;     const int c = lane & 7;
; #pragma unroll
;     for (int j = 0; j < 4; ++j) { const int n = (lane >> 3) + 8 * j; const LAS float* s = scr + (8 * c) * 33 + n;
;         u32x4 o; o.x = cvt_pk_bf16(s[0 * 33], s[1 * 33]); o.y = cvt_pk_bf16(s[2 * 33], s[3 * 33]); o.z = cvt_pk_bf16(s[4 * 33], s[5 * 33]); o.w = cvt_pk_bf16(s[6 * 33], s[7 * 33]);
;         *(u32x4*)(WT + (size_t)(n0 + n) * K + k0 + 8 * c) = o; }
;     LDS_WAIT(); asm volatile("" ::: "memory");
	v_mul_f32_e32 v48, v49, v48
	ds_write_b32 v6, v48
	v_mul_f32_e32 v51, v50, v51
	ds_write_b32 v6, v51 offset:264
	v_mul_f32_e32 v53, v52, v53
	ds_write_b32 v6, v53 offset:528
	v_mul_f32_e32 v55, v54, v55
	ds_write_b32 v6, v55 offset:792
	v_mul_f32_e32 v56, v57, v56
	ds_write_b32 v6, v56 offset:1056
	v_mul_f32_e32 v59, v58, v59
	ds_write_b32 v6, v59 offset:1320
	v_mul_f32_e32 v61, v60, v61
	ds_write_b32 v6, v61 offset:1584
	v_mul_f32_e32 v63, v62, v63
	ds_write_b32 v6, v63 offset:1848
	v_mul_f32_e32 v64, v65, v64
	ds_write_b32 v6, v64 offset:2112
	v_mul_f32_e32 v67, v66, v67
	ds_write_b32 v6, v67 offset:2376
	v_mul_f32_e32 v69, v68, v69
	ds_write_b32 v6, v69 offset:2640
	v_mul_f32_e32 v71, v70, v71
	ds_write_b32 v6, v71 offset:2904
	v_mul_f32_e32 v72, v73, v72
	ds_write_b32 v6, v72 offset:3168
	v_mul_f32_e32 v75, v74, v75
	ds_write_b32 v6, v75 offset:3432
	v_mul_f32_e32 v77, v76, v77
	ds_write_b32 v6, v77 offset:3696
	v_mul_f32_e32 v79, v78, v79
	ds_write_b32 v6, v79 offset:3960
	v_mul_f32_e32 v80, v81, v80
	ds_write_b32 v6, v80 offset:4224
	v_mul_f32_e32 v83, v82, v83
	ds_write_b32 v6, v83 offset:4488
	v_mul_f32_e32 v85, v84, v85
	ds_write_b32 v6, v85 offset:4752
	v_mul_f32_e32 v87, v86, v87
	ds_write_b32 v6, v87 offset:5016
	v_mul_f32_e32 v88, v89, v88
	ds_write_b32 v6, v88 offset:5280
	v_mul_f32_e32 v91, v90, v91
	ds_write_b32 v6, v91 offset:5544
	v_mul_f32_e32 v93, v92, v93
	ds_write_b32 v6, v93 offset:5808
	v_mul_f32_e32 v95, v94, v95
	ds_write_b32 v6, v95 offset:6072
	v_mul_f32_e32 v96, v97, v96
	ds_write_b32 v6, v96 offset:6336
	v_mul_f32_e32 v99, v98, v99
	ds_write_b32 v6, v99 offset:6600
	v_mul_f32_e32 v101, v100, v101
	ds_write_b32 v6, v101 offset:6864
	v_mul_f32_e32 v103, v102, v103
	ds_write_b32 v6, v103 offset:7128
	v_mul_f32_e32 v104, v105, v104
	ds_write_b32 v6, v104 offset:7392
	v_mul_f32_e32 v107, v106, v107
	ds_write_b32 v6, v107 offset:7656
	v_mul_f32_e32 v109, v108, v109
	ds_write_b32 v6, v109 offset:7920
	v_mul_f32_e32 v111, v110, v111
	ds_write_b32 v6, v111 offset:8184
	v_add_u32_e32 v6, 0x2100, v6
	s_cbranch_scc1 .LBB0_78
	s_and_b32 s4, 0xffff, s37
	s_waitcnt lgkmcnt(0)
	s_lshl_b32 s4, s4, 1
	s_add_u32 s4, s67, s4
	ds_read2_b32 v[12:13], v25 offset1:33
	v_mov_b32_e32 v11, v7
	v_add_u32_e32 v16, s12, v24
	s_addc_u32 s5, s66, 0
	s_waitcnt lgkmcnt(0)
	v_cvt_pk_bf16_f32 v12, v12, v13
	ds_read2_b32 v[14:15], v25 offset0:66 offset1:99
	v_ashrrev_i32_e32 v17, 31, v16
	v_lshl_add_u64 v[20:21], s[4:5], 0, v[10:11]
	s_waitcnt lgkmcnt(0)
	v_cvt_pk_bf16_f32 v13, v14, v15
	ds_read2_b32 v[14:15], v25 offset0:132 offset1:165
	v_lshlrev_b64 v[16:17], 11, v[16:17]
	v_lshl_add_u64 v[20:21], v[20:21], 0, s[34:35]
	s_waitcnt lgkmcnt(0)
	v_cvt_pk_bf16_f32 v14, v14, v15
	ds_read2_b32 v[18:19], v25 offset0:198 offset1:231
	v_lshl_add_u64 v[16:17], v[20:21], 0, v[16:17]
	s_waitcnt lgkmcnt(0)
	v_cvt_pk_bf16_f32 v15, v18, v19
	flat_store_dwordx4 v[16:17], v[12:15]
	v_add_u32_e32 v18, s12, v26
	ds_read2_b32 v[12:13], v25 offset0:8 offset1:41
	v_ashrrev_i32_e32 v19, 31, v18
	s_waitcnt lgkmcnt(0)
	v_cvt_pk_bf16_f32 v12, v12, v13
	ds_read2_b32 v[14:15], v25 offset0:74 offset1:107
	v_lshlrev_b64 v[18:19], 11, v[18:19]
	s_waitcnt lgkmcnt(0)
	v_cvt_pk_bf16_f32 v13, v14, v15
	ds_read2_b32 v[14:15], v25 offset0:140 offset1:173
	v_lshl_add_u64 v[18:19], v[20:21], 0, v[18:19]
	s_waitcnt lgkmcnt(0)
	v_cvt_pk_bf16_f32 v14, v14, v15
	ds_read2_b32 v[16:17], v25 offset0:206 offset1:239
	s_waitcnt lgkmcnt(0)
	v_cvt_pk_bf16_f32 v15, v16, v17
	flat_store_dwordx4 v[18:19], v[12:15]
	v_add_u32_e32 v18, s12, v27
	ds_read2_b32 v[12:13], v25 offset0:16 offset1:49
	v_ashrrev_i32_e32 v19, 31, v18
	s_waitcnt lgkmcnt(0)
	v_cvt_pk_bf16_f32 v12, v12, v13
	ds_read2_b32 v[14:15], v25 offset0:82 offset1:115
	v_lshlrev_b64 v[18:19], 11, v[18:19]
	s_waitcnt lgkmcnt(0)
	v_cvt_pk_bf16_f32 v13, v14, v15
	ds_read2_b32 v[14:15], v25 offset0:148 offset1:181
	v_lshl_add_u64 v[18:19], v[20:21], 0, v[18:19]
	s_waitcnt lgkmcnt(0)
	v_cvt_pk_bf16_f32 v14, v14, v15
	ds_read2_b32 v[16:17], v25 offset0:214 offset1:247
	s_waitcnt lgkmcnt(0)
	v_cvt_pk_bf16_f32 v15, v16, v17
	flat_store_dwordx4 v[18:19], v[12:15]
	ds_read2_b32 v[12:13], v25 offset0:24 offset1:57
	v_add_u32_e32 v18, s12, v28
	s_waitcnt lgkmcnt(0)
	v_cvt_pk_bf16_f32 v12, v12, v13
	ds_read2_b32 v[14:15], v25 offset0:90 offset1:123
	s_waitcnt lgkmcnt(0)
	v_cvt_pk_bf16_f32 v13, v14, v15
	ds_read2_b32 v[14:15], v25 offset0:156 offset1:189
	v_ashrrev_i32_e32 v19, 31, v18
	s_waitcnt lgkmcnt(0)
	v_cvt_pk_bf16_f32 v14, v14, v15
	ds_read2_b32 v[16:17], v25 offset0:222 offset1:255
	v_lshlrev_b64 v[18:19], 11, v[18:19]
	s_waitcnt lgkmcnt(0)
	v_cvt_pk_bf16_f32 v15, v16, v17
	v_lshl_add_u64 v[16:17], v[20:21], 0, v[18:19]
	flat_store_dwordx4 v[16:17], v[12:15]
	s_waitcnt lgkmcnt(0)

; __device__ __forceinline__ float wval(KArg ka, int mat, int l, int k, int n) {
;     ...
;     case M_IN:   return n < INW ? PIN(I_WIN)[((size_t)l * 1024 + k) * INW + n] * PIN(I_LMPRE)[l * 1024 + k] : 0.f;
; __device__ __forceinline__ void tr_item(KArg ka, int mat, int l, int K, bf16_t* WT, LAS float* scr, int kb, int nb, int lane) {
;     const int k0 = 64 * kb, n0 = 32 * nb;
; #pragma unroll 4
;     for (int i = 0; i < 32; ++i) { const int kk = 2 * i + (lane >> 5); scr[kk * 33 + (lane & 31)] = wval(ka, mat, l, k0 + kk, n0 + (lane & 31)); }
.LBB0_96:
	v_lshl_add_u64 v[40:41], v[20:21], 0, s[4:5]
	global_load_dword v48, v[22:23], off
	global_load_dword v49, v[40:41], off
	v_lshl_add_u64 v[40:41], v[18:19], 0, s[4:5]
	v_add_u32_e32 v42, -2, v12
	v_ashrrev_i32_e32 v43, 31, v42
	v_lshlrev_b64 v[42:43], 12, v[42:43]
	v_lshl_add_u64 v[42:43], v[14:15], 0, v[42:43]
	s_add_u32 s4, s4, 32
	s_addc_u32 s5, s5, 0
	v_lshl_add_u64 v[22:23], v[22:23], 0, s[14:15]
	s_cmpk_lg_i32 s4, 0x100
	global_load_dword v50, v[16:17], off
	global_load_dword v51, v[40:41], off offset:8
	v_lshl_add_u64 v[16:17], v[16:17], 0, s[14:15]
	global_load_dword v52, v[42:43], off
	global_load_dword v53, v[40:41], off offset:16
	v_ashrrev_i32_e32 v13, 31, v12
	v_lshlrev_b64 v[42:43], 12, v[12:13]
	v_lshl_add_u64 v[42:43], v[14:15], 0, v[42:43]
	v_add_u32_e32 v12, 8, v12
	global_load_dword v54, v[42:43], off
	global_load_dword v55, v[40:41], off offset:24
	v_lshl_add_u64 v[40:41], v[20:21], 0, s[4:5]
	global_load_dword v56, v[22:23], off
	global_load_dword v57, v[40:41], off
	v_lshl_add_u64 v[40:41], v[18:19], 0, s[4:5]
	v_add_u32_e32 v42, -2, v12
	v_ashrrev_i32_e32 v43, 31, v42
	v_lshlrev_b64 v[42:43], 12, v[42:43]
	v_lshl_add_u64 v[42:43], v[14:15], 0, v[42:43]
	s_add_u32 s4, s4, 32
	s_addc_u32 s5, s5, 0
	v_lshl_add_u64 v[22:23], v[22:23], 0, s[14:15]
	s_cmpk_lg_i32 s4, 0x100
	global_load_dword v58, v[16:17], off
	global_load_dword v59, v[40:41], off offset:8
	v_lshl_add_u64 v[16:17], v[16:17], 0, s[14:15]
	global_load_dword v60, v[42:43], off
	global_load_dword v61, v[40:41], off offset:16
	v_ashrrev_i32_e32 v13, 31, v12
	v_lshlrev_b64 v[42:43], 12, v[12:13]
	v_lshl_add_u64 v[42:43], v[14:15], 0, v[42:43]
	v_add_u32_e32 v12, 8, v12
	global_load_dword v62, v[42:43], off
	global_load_dword v63, v[40:41], off offset:24
	v_lshl_add_u64 v[40:41], v[20:21], 0, s[4:5]
	global_load_dword v64, v[22:23], off
	global_load_dword v65, v[40:41], off
	v_lshl_add_u64 v[40:41], v[18:19], 0, s[4:5]
	v_add_u32_e32 v42, -2, v12
	v_ashrrev_i32_e32 v43, 31, v42
	v_lshlrev_b64 v[42:43], 12, v[42:43]
	v_lshl_add_u64 v[42:43], v[14:15], 0, v[42:43]
	s_add_u32 s4, s4, 32
	s_addc_u32 s5, s5, 0
	v_lshl_add_u64 v[22:23], v[22:23], 0, s[14:15]
	s_cmpk_lg_i32 s4, 0x100
	global_load_dword v66, v[16:17], off
	global_load_dword v67, v[40:41], off offset:8
	v_lshl_add_u64 v[16:17], v[16:17], 0, s[14:15]
	global_load_dword v68, v[42:43], off
	global_load_dword v69, v[40:41], off offset:16
	v_ashrrev_i32_e32 v13, 31, v12
	v_lshlrev_b64 v[42:43], 12, v[12:13]
	v_lshl_add_u64 v[42:43], v[14:15], 0, v[42:43]
	v_add_u32_e32 v12, 8, v12
	global_load_dword v70, v[42:43], off
	global_load_dword v71, v[40:41], off offset:24
	v_lshl_add_u64 v[40:41], v[20:21], 0, s[4:5]
	global_load_dword v72, v[22:23], off
	global_load_dword v73, v[40:41], off
	v_lshl_add_u64 v[40:41], v[18:19], 0, s[4:5]
	v_add_u32_e32 v42, -2, v12
	v_ashrrev_i32_e32 v43, 31, v42
	v_lshlrev_b64 v[42:43], 12, v[42:43]
	v_lshl_add_u64 v[42:43], v[14:15], 0, v[42:43]
	s_add_u32 s4, s4, 32
	s_addc_u32 s5, s5, 0
	v_lshl_add_u64 v[22:23], v[22:23], 0, s[14:15]
	s_cmpk_lg_i32 s4, 0x100
	global_load_dword v74, v[16:17], off
	global_load_dword v75, v[40:41], off offset:8
	v_lshl_add_u64 v[16:17], v[16:17], 0, s[14:15]
	global_load_dword v76, v[42:43], off
	global_load_dword v77, v[40:41], off offset:16
	v_ashrrev_i32_e32 v13, 31, v12
	v_lshlrev_b64 v[42:43], 12, v[12:13]
	v_lshl_add_u64 v[42:43], v[14:15], 0, v[42:43]
	v_add_u32_e32 v12, 8, v12
	global_load_dword v78, v[42:43], off
	global_load_dword v79, v[40:41], off offset:24
	v_lshl_add_u64 v[40:41], v[20:21], 0, s[4:5]
	global_load_dword v80, v[22:23], off
	global_load_dword v81, v[40:41], off
	v_lshl_add_u64 v[40:41], v[18:19], 0, s[4:5]
	v_add_u32_e32 v42, -2, v12
	v_ashrrev_i32_e32 v43, 31, v42
	v_lshlrev_b64 v[42:43], 12, v[42:43]
	v_lshl_add_u64 v[42:43], v[14:15], 0, v[42:43]
	s_add_u32 s4, s4, 32
	s_addc_u32 s5, s5, 0
	v_lshl_add_u64 v[22:23], v[22:23], 0, s[14:15]
	s_cmpk_lg_i32 s4, 0x100
	global_load_dword v82, v[16:17], off
	global_load_dword v83, v[40:41], off offset:8
	v_lshl_add_u64 v[16:17], v[16:17], 0, s[14:15]
	global_load_dword v84, v[42:43], off
	global_load_dword v85, v[40:41], off offset:16
	v_ashrrev_i32_e32 v13, 31, v12
	v_lshlrev_b64 v[42:43], 12, v[12:13]
	v_lshl_add_u64 v[42:43], v[14:15], 0, v[42:43]
	v_add_u32_e32 v12, 8, v12
	global_load_dword v86, v[42:43], off
	global_load_dword v87, v[40:41], off offset:24
	v_lshl_add_u64 v[40:41], v[20:21], 0, s[4:5]
	global_load_dword v88, v[22:23], off
	global_load_dword v89, v[40:41], off
	v_lshl_add_u64 v[40:41], v[18:19], 0, s[4:5]
	v_add_u32_e32 v42, -2, v12
	v_ashrrev_i32_e32 v43, 31, v42
	v_lshlrev_b64 v[42:43], 12, v[42:43]
	v_lshl_add_u64 v[42:43], v[14:15], 0, v[42:43]
	s_add_u32 s4, s4, 32
	s_addc_u32 s5, s5, 0
	v_lshl_add_u64 v[22:23], v[22:23], 0, s[14:15]
	s_cmpk_lg_i32 s4, 0x100
	global_load_dword v90, v[16:17], off
	global_load_dword v91, v[40:41], off offset:8
	v_lshl_add_u64 v[16:17], v[16:17], 0, s[14:15]
	global_load_dword v92, v[42:43], off
	global_load_dword v93, v[40:41], off offset:16
	v_ashrrev_i32_e32 v13, 31, v12
	v_lshlrev_b64 v[42:43], 12, v[12:13]
	v_lshl_add_u64 v[42:43], v[14:15], 0, v[42:43]
	v_add_u32_e32 v12, 8, v12
	global_load_dword v94, v[42:43], off
	global_load_dword v95, v[40:41], off offset:24
	v_lshl_add_u64 v[40:41], v[20:21], 0, s[4:5]
	global_load_dword v96, v[22:23], off
	global_load_dword v97, v[40:41], off
	v_lshl_add_u64 v[40:41], v[18:19], 0, s[4:5]
	v_add_u32_e32 v42, -2, v12
	v_ashrrev_i32_e32 v43, 31, v42
	v_lshlrev_b64 v[42:43], 12, v[42:43]
	v_lshl_add_u64 v[42:43], v[14:15], 0, v[42:43]
	s_add_u32 s4, s4, 32
; __device__ __forceinline__ unsigned cvt_pk_bf16(float lo, float hi) { unsigned r; asm volatile("v_cvt_pk_bf16_f32 %0, %1, %2" : "=v"(r) : "v"(lo), "v"(hi)); return r; }
; #define LAS __attribute__((address_space(3)))
; #define LDS_WAIT() asm volatile("s_waitcnt lgkmcnt(0)" ::: "memory")
; __device__ __forceinline__ void tr_item(KArg ka, int mat, int l, int K, bf16_t* WT, LAS float* scr, int kb, int nb, int lane) {
;     const int k0 = 64 * kb, n0 = 32 * nb;
; #pragma unroll 4
;     for (int i = 0; i < 32; ++i) { const int kk = 2 * i + (lane >> 5); scr[kk * 33 + (lane & 31)] = wval(ka, mat, l, k0 + kk, n0 + (lane & 31)); }
;     LDS_WAIT(); asm volatile("" ::: "memory");
;     const int c = lane & 7;
; #pragma unroll
;     for (int j = 0; j < 4; ++j) { const int n = (lane >> 3) + 8 * j; const LAS float* s = scr + (8 * c) * 33 + n;
;         u32x4 o; o.x = cvt_pk_bf16(s[0 * 33], s[1 * 33]); o.y = cvt_pk_bf16(s[2 * 33], s[3 * 33]); o.z = cvt_pk_bf16(s[4 * 33], s[5 * 33]); o.w = cvt_pk_bf16(s[6 * 33], s[7 * 33]);
;         *(u32x4*)(WT + (size_t)(n0 + n) * K + k0 + 8 * c) = o; }
;     LDS_WAIT(); asm volatile("" ::: "memory");
	s_addc_u32 s5, s5, 0
	v_lshl_add_u64 v[22:23], v[22:23], 0, s[14:15]
	s_cmpk_lg_i32 s4, 0x100
	global_load_dword v98, v[16:17], off
	global_load_dword v99, v[40:41], off offset:8
	v_lshl_add_u64 v[16:17], v[16:17], 0, s[14:15]
	global_load_dword v100, v[42:43], off
	global_load_dword v101, v[40:41], off offset:16
	v_ashrrev_i32_e32 v13, 31, v12
	v_lshlrev_b64 v[42:43], 12, v[12:13]
	v_lshl_add_u64 v[42:43], v[14:15], 0, v[42:43]
	v_add_u32_e32 v12, 8, v12
	global_load_dword v102, v[42:43], off
	global_load_dword v103, v[40:41], off offset:24
	v_lshl_add_u64 v[40:41], v[20:21], 0, s[4:5]
	global_load_dword v104, v[22:23], off
	global_load_dword v105, v[40:41], off
	v_lshl_add_u64 v[40:41], v[18:19], 0, s[4:5]
	v_add_u32_e32 v42, -2, v12
	v_ashrrev_i32_e32 v43, 31, v42
	v_lshlrev_b64 v[42:43], 12, v[42:43]
	v_lshl_add_u64 v[42:43], v[14:15], 0, v[42:43]
	s_add_u32 s4, s4, 32
	s_addc_u32 s5, s5, 0
	v_lshl_add_u64 v[22:23], v[22:23], 0, s[14:15]
	s_cmpk_lg_i32 s4, 0x100
	global_load_dword v106, v[16:17], off
	global_load_dword v107, v[40:41], off offset:8
	v_lshl_add_u64 v[16:17], v[16:17], 0, s[14:15]
	global_load_dword v108, v[42:43], off
	global_load_dword v109, v[40:41], off offset:16
	v_ashrrev_i32_e32 v13, 31, v12
	v_lshlrev_b64 v[42:43], 12, v[12:13]
	v_lshl_add_u64 v[42:43], v[14:15], 0, v[42:43]
	v_add_u32_e32 v12, 8, v12
	global_load_dword v110, v[42:43], off
	global_load_dword v111, v[40:41], off offset:24
	s_waitcnt vmcnt(0)
	v_mul_f32_e32 v49, v48, v49
	ds_write_b32 v6, v49
	v_mul_f32_e32 v51, v50, v51
	ds_write_b32 v6, v51 offset:264
	v_mul_f32_e32 v53, v52, v53
	ds_write_b32 v6, v53 offset:528
	v_mul_f32_e32 v55, v54, v55
	ds_write_b32 v6, v55 offset:792
	v_mul_f32_e32 v57, v56, v57
	ds_write_b32 v6, v57 offset:1056
	v_mul_f32_e32 v59, v58, v59
	ds_write_b32 v6, v59 offset:1320
	v_mul_f32_e32 v61, v60, v61
	ds_write_b32 v6, v61 offset:1584
	v_mul_f32_e32 v63, v62, v63
	ds_write_b32 v6, v63 offset:1848
	v_mul_f32_e32 v65, v64, v65
	ds_write_b32 v6, v65 offset:2112
	v_mul_f32_e32 v67, v66, v67
	ds_write_b32 v6, v67 offset:2376
	v_mul_f32_e32 v69, v68, v69
	ds_write_b32 v6, v69 offset:2640
	v_mul_f32_e32 v71, v70, v71
	ds_write_b32 v6, v71 offset:2904
	v_mul_f32_e32 v73, v72, v73
	ds_write_b32 v6, v73 offset:3168
	v_mul_f32_e32 v75, v74, v75
	ds_write_b32 v6, v75 offset:3432
	v_mul_f32_e32 v77, v76, v77
	ds_write_b32 v6, v77 offset:3696
	v_mul_f32_e32 v79, v78, v79
	ds_write_b32 v6, v79 offset:3960
	v_mul_f32_e32 v81, v80, v81
	ds_write_b32 v6, v81 offset:4224
	v_mul_f32_e32 v83, v82, v83
	ds_write_b32 v6, v83 offset:4488
	v_mul_f32_e32 v85, v84, v85
	ds_write_b32 v6, v85 offset:4752
	v_mul_f32_e32 v87, v86, v87
	ds_write_b32 v6, v87 offset:5016
	v_mul_f32_e32 v89, v88, v89
	ds_write_b32 v6, v89 offset:5280
	v_mul_f32_e32 v91, v90, v91
	ds_write_b32 v6, v91 offset:5544
	v_mul_f32_e32 v93, v92, v93
	ds_write_b32 v6, v93 offset:5808
	v_mul_f32_e32 v95, v94, v95
	ds_write_b32 v6, v95 offset:6072
	v_mul_f32_e32 v97, v96, v97
	ds_write_b32 v6, v97 offset:6336
	v_mul_f32_e32 v99, v98, v99
	ds_write_b32 v6, v99 offset:6600
	v_mul_f32_e32 v101, v100, v101
	ds_write_b32 v6, v101 offset:6864
	v_mul_f32_e32 v103, v102, v103
	ds_write_b32 v6, v103 offset:7128
	v_mul_f32_e32 v105, v104, v105
	ds_write_b32 v6, v105 offset:7392
	v_mul_f32_e32 v107, v106, v107
	ds_write_b32 v6, v107 offset:7656
	v_mul_f32_e32 v109, v108, v109
	ds_write_b32 v6, v109 offset:7920
	v_mul_f32_e32 v111, v110, v111
	ds_write_b32 v6, v111 offset:8184
	v_add_u32_e32 v6, 0x2100, v6
	s_cbranch_scc1 .LBB0_96
	s_waitcnt lgkmcnt(0)
	ds_read2_b32 v[12:13], v25 offset1:33
	v_add_u32_e32 v16, s36, v24
	s_waitcnt lgkmcnt(0)
	v_cvt_pk_bf16_f32 v12, v12, v13
	ds_read2_b32 v[14:15], v25 offset0:66 offset1:99
	s_and_b32 s12, s12, 0xffffff80
	v_ashrrev_i32_e32 v17, 31, v16
	s_waitcnt lgkmcnt(0)
	v_cvt_pk_bf16_f32 v13, v14, v15
	ds_read2_b32 v[14:15], v25 offset0:132 offset1:165
	v_lshl_add_u64 v[20:21], v[8:9], 0, s[12:13]
	v_lshlrev_b64 v[16:17], 11, v[16:17]
	s_waitcnt lgkmcnt(0)
	v_cvt_pk_bf16_f32 v14, v14, v15
	ds_read2_b32 v[18:19], v25 offset0:198 offset1:231
	v_lshl_add_u64 v[16:17], v[20:21], 0, v[16:17]
	s_waitcnt lgkmcnt(0)
	v_cvt_pk_bf16_f32 v15, v18, v19
	flat_store_dwordx4 v[16:17], v[12:15]
	v_add_u32_e32 v18, s36, v26
	ds_read2_b32 v[12:13], v25 offset0:8 offset1:41
	v_ashrrev_i32_e32 v19, 31, v18
	s_waitcnt lgkmcnt(0)
	v_cvt_pk_bf16_f32 v12, v12, v13
	ds_read2_b32 v[14:15], v25 offset0:74 offset1:107
	v_lshlrev_b64 v[18:19], 11, v[18:19]
	s_waitcnt lgkmcnt(0)
	v_cvt_pk_bf16_f32 v13, v14, v15
	ds_read2_b32 v[14:15], v25 offset0:140 offset1:173
	v_lshl_add_u64 v[18:19], v[20:21], 0, v[18:19]
	s_waitcnt lgkmcnt(0)
	v_cvt_pk_bf16_f32 v14, v14, v15
	ds_read2_b32 v[16:17], v25 offset0:206 offset1:239
	s_waitcnt lgkmcnt(0)
	v_cvt_pk_bf16_f32 v15, v16, v17
	flat_store_dwordx4 v[18:19], v[12:15]
	v_add_u32_e32 v18, s36, v27
	ds_read2_b32 v[12:13], v25 offset0:16 offset1:49
	v_ashrrev_i32_e32 v19, 31, v18
	s_waitcnt lgkmcnt(0)
	v_cvt_pk_bf16_f32 v12, v12, v13
	ds_read2_b32 v[14:15], v25 offset0:82 offset1:115
	v_lshlrev_b64 v[18:19], 11, v[18:19]
	s_waitcnt lgkmcnt(0)
	v_cvt_pk_bf16_f32 v13, v14, v15
	ds_read2_b32 v[14:15], v25 offset0:148 offset1:181
	v_lshl_add_u64 v[18:19], v[20:21], 0, v[18:19]
	s_waitcnt lgkmcnt(0)
	v_cvt_pk_bf16_f32 v14, v14, v15
	ds_read2_b32 v[16:17], v25 offset0:214 offset1:247
	s_waitcnt lgkmcnt(0)
	v_cvt_pk_bf16_f32 v15, v16, v17
	flat_store_dwordx4 v[18:19], v[12:15]
	ds_read2_b32 v[12:13], v25 offset0:24 offset1:57
	v_add_u32_e32 v18, s36, v28
	s_waitcnt lgkmcnt(0)
	v_cvt_pk_bf16_f32 v12, v12, v13
	ds_read2_b32 v[14:15], v25 offset0:90 offset1:123
	s_waitcnt lgkmcnt(0)
	v_cvt_pk_bf16_f32 v13, v14, v15
	ds_read2_b32 v[14:15], v25 offset0:156 offset1:189
	v_ashrrev_i32_e32 v19, 31, v18
	s_waitcnt lgkmcnt(0)
	v_cvt_pk_bf16_f32 v14, v14, v15
	ds_read2_b32 v[16:17], v25 offset0:222 offset1:255
	v_lshlrev_b64 v[18:19], 11, v[18:19]
	s_waitcnt lgkmcnt(0)
	v_cvt_pk_bf16_f32 v15, v16, v17
	v_lshl_add_u64 v[16:17], v[20:21], 0, v[18:19]
	flat_store_dwordx4 v[16:17], v[12:15]
	s_waitcnt lgkmcnt(0)
	s_branch .LBB0_9

; #define GASF __attribute__((address_space(1)))
; __device__ __forceinline__ void resid_rows(const float* xf_, bf16_t* XB_, const bf16_t* Y_, const float* gain_, float* R_, float* outf_, int rows, int gw, int NGW, int lane) {
;     u32x4 xw[2], yw[2], nxw[2], nyw[2]; f32x4 xv[4], nxv[4];
;     const int last = rows - 1;
;     ...
;     RR_LOAD(xw, yw, xv, gw);
;     for (int row = gw; row < rows; row += NGW) {
;     ...
;             const GASF f32x4* gp = (const GASF f32x4*)gain_;
; #pragma unroll
;             for (int j = 0; j < 2; ++j) { const f32x4 a = gp[lane * 2 + 128 * j], b = gp[lane * 2 + 1 + 128 * j];
.LBB0_195:
	s_load_dwordx2 s[12:13], s[14:15], 0xc8
	s_lshl_b32 s2, s2, 3
	v_mbcnt_lo_u32_b32 v0, -1, v0
	s_add_i32 s0, s2, s0
	s_lshl_b32 s2, s1, 3
	v_readlane_b32 s1, v255, 41
	s_cmp_lg_u32 s1, 0
	v_mbcnt_hi_u32_b32 v64, -1, v0
	s_cbranch_scc0 .LBB0_202
	s_cmpk_gt_i32 s0, 0x7fff
	s_cbranch_scc1 .LBB0_201
	s_waitcnt lgkmcnt(0)
	s_add_u32 s4, s12, 0x19800000
	s_addc_u32 s5, s13, 0
	s_add_u32 s7, s12, 0x2c800000
	s_addc_u32 s8, s13, 0
	s_ashr_i32 s1, s0, 31
	s_lshl_b64 s[16:17], s[0:1], 11
	s_add_u32 s18, s7, s16
	s_addc_u32 s19, s8, s17
	v_ashrrev_i32_e32 v65, 31, v64
	s_add_u32 s16, s4, s16
	v_lshlrev_b64 v[24:25], 4, v[64:65]
	s_addc_u32 s17, s5, s17
	v_lshl_add_u64 v[0:1], s[18:19], 0, v[24:25]
	v_lshl_add_u64 v[8:9], s[16:17], 0, v[24:25]
	global_load_dwordx4 v[4:7], v[0:1], off offset:1024
	global_load_dwordx4 v[12:15], v[0:1], off
	s_nop 0
	global_load_dwordx4 v[0:3], v[8:9], off offset:1024
	s_nop 0
	global_load_dwordx4 v[8:11], v[8:9], off
	s_load_dwordx2 s[18:19], s[14:15], 0xa8
	v_readlane_b32 s3, v255, 41
	s_lshl_b32 s10, s3, 10
	s_lshl_b64 s[20:21], s[10:11], 2
	v_lshlrev_b32_e32 v16, 1, v64
	s_waitcnt lgkmcnt(0)
	s_add_u32 s18, s18, s20
	s_addc_u32 s19, s19, s21
	v_ashrrev_i32_e32 v17, 31, v16
	v_lshl_add_u64 v[16:17], v[16:17], 4, s[18:19]
	s_movk_i32 s18, 0xf000
	s_mov_b32 s19, -1
	v_lshl_add_u64 v[26:27], v[16:17], 0, s[18:19]
	s_lshl_b64 s[18:19], s[0:1], 2
	s_add_u32 s1, s12, s18
	s_addc_u32 s3, s13, s19
	s_add_u32 s18, s1, 0x30840000
	s_addc_u32 s19, s3, 0
	s_ashr_i32 s3, s2, 31
	v_cmp_eq_u32_e64 s[40:41], 0, v64
	s_lshl_b64 s[20:21], s[2:3], 2
	s_lshl_b64 s[22:23], s[2:3], 11
	s_mov_b32 s1, s0
	global_load_dwordx4 v[68:71], v[26:27], off
	global_load_dwordx4 v[72:75], v[26:27], off offset:16
	global_load_dwordx4 v[76:79], v[26:27], off offset:2048
	global_load_dwordx4 v[80:83], v[26:27], off offset:2064
	s_waitcnt vmcnt(0)
	s_branch .LBB0_199

; __device__ __forceinline__ void resid_rows(const float* xf_, bf16_t* XB_, const bf16_t* Y_, const float* gain_, float* R_, float* outf_, int rows, int gw, int NGW, int lane) {
;     ...
;     for (int row = gw; row < rows; row += NGW) {
;         RR_LOAD(nxw, nyw, nxv, row + NGW);
;         float v[16];
;         if (xf_) {
; #pragma unroll
;             for (int j = 0; j < 2; ++j) { const f32x4 a = xv[2 * j], b = xv[2 * j + 1];
;                 v[8 * j + 0] = a.x; v[8 * j + 1] = a.y; v[8 * j + 2] = a.z; v[8 * j + 3] = a.w; v[8 * j + 4] = b.x; v[8 * j + 5] = b.y; v[8 * j + 6] = b.z; v[8 * j + 7] = b.w; } }
;         else {
; #pragma unroll
;             for (int j = 0; j < 2; ++j) { const u32x4 w = xw[j];
;                 v[8 * j + 0] = bf_lo(w.x); v[8 * j + 1] = bf_hi(w.x); v[8 * j + 2] = bf_lo(w.y); v[8 * j + 3] = bf_hi(w.y); v[8 * j + 4] = bf_lo(w.z); v[8 * j + 5] = bf_hi(w.z); v[8 * j + 6] = bf_lo(w.w); v[8 * j + 7] = bf_hi(w.w); } }
;         if (Y_) { float y[16]; float ss = 0.f;
; #pragma unroll
;             for (int j = 0; j < 2; ++j) { const u32x4 w = yw[j];
;                 y[8 * j + 0] = bf_lo(w.x); y[8 * j + 1] = bf_hi(w.x); y[8 * j + 2] = bf_lo(w.y); y[8 * j + 3] = bf_hi(w.y); y[8 * j + 4] = bf_lo(w.z); y[8 * j + 5] = bf_hi(w.z); y[8 * j + 6] = bf_lo(w.w); y[8 * j + 7] = bf_hi(w.w); }
; #pragma unroll
;             for (int i = 0; i < 16; ++i) ss += y[i] * y[i];
;             const float r = 1.0f / sqrtf(wave_sum(ss) * (1.f / DM) + EPS);
;             const GASF f32x4* gp = (const GASF f32x4*)gain_;
; #pragma unroll
;             for (int j = 0; j < 2; ++j) { const f32x4 a = gp[lane * 2 + 128 * j], b = gp[lane * 2 + 1 + 128 * j];
;                 v[8 * j + 0] += y[8 * j + 0] * r * a.x; v[8 * j + 1] += y[8 * j + 1] * r * a.y; v[8 * j + 2] += y[8 * j + 2] * r * a.z; v[8 * j + 3] += y[8 * j + 3] * r * a.w;
;                 v[8 * j + 4] += y[8 * j + 4] * r * b.x; v[8 * j + 5] += y[8 * j + 5] * r * b.y; v[8 * j + 6] += y[8 * j + 6] * r * b.z; v[8 * j + 7] += y[8 * j + 7] * r * b.w; } }
;         if (outf_) { GASF f32x4* p = (GASF f32x4*)(outf_ + (size_t)row * DM);
; #pragma unroll
;             for (int j = 0; j < 2; ++j) { p[lane * 2 + 128 * j] = (f32x4){v[8 * j + 0], v[8 * j + 1], v[8 * j + 2], v[8 * j + 3]}; p[lane * 2 + 1 + 128 * j] = (f32x4){v[8 * j + 4], v[8 * j + 5], v[8 * j + 6], v[8 * j + 7]}; } }
.LBB0_199:
	s_waitcnt vmcnt(3)
	v_mov_b64_e32 v[18:19], v[14:15]
	v_mov_b64_e32 v[16:17], v[12:13]
	v_and_b32_e32 v54, 0xffff0000, v16
	v_lshlrev_b32_e32 v53, 16, v16
	v_mul_f32_e32 v16, v54, v54
	v_lshlrev_b32_e32 v55, 16, v17
	v_fmac_f32_e32 v16, v53, v53
	v_and_b32_e32 v56, 0xffff0000, v17
	v_fmac_f32_e32 v16, v55, v55
	v_lshlrev_b32_e32 v57, 16, v18
	v_fmac_f32_e32 v16, v56, v56
	v_and_b32_e32 v58, 0xffff0000, v18
	v_fmac_f32_e32 v16, v57, v57
	v_mov_b64_e32 v[22:23], v[6:7]
	v_lshlrev_b32_e32 v59, 16, v19
	v_fmac_f32_e32 v16, v58, v58
	v_mov_b64_e32 v[20:21], v[4:5]
	v_and_b32_e32 v60, 0xffff0000, v19
	v_fmac_f32_e32 v16, v59, v59
	v_lshlrev_b32_e32 v51, 16, v20
	v_fmac_f32_e32 v16, v60, v60
	v_and_b32_e32 v50, 0xffff0000, v20
	v_fmac_f32_e32 v16, v51, v51
	v_mov_b64_e32 v[30:31], v[10:11]
	v_lshlrev_b32_e32 v49, 16, v21
	v_fmac_f32_e32 v16, v50, v50
	v_mov_b64_e32 v[28:29], v[8:9]
	v_mov_b64_e32 v[46:47], v[2:3]
	v_and_b32_e32 v48, 0xffff0000, v21
	v_fmac_f32_e32 v16, v49, v49
	v_lshlrev_b32_e32 v41, 16, v28
	v_and_b32_e32 v43, 0xffff0000, v28
	v_lshlrev_b32_e32 v42, 16, v29
	v_and_b32_e32 v40, 0xffff0000, v29
	v_lshlrev_b32_e32 v29, 16, v47
	v_and_b32_e32 v28, 0xffff0000, v47
	v_lshlrev_b32_e32 v47, 16, v22
	v_fmac_f32_e32 v16, v48, v48
	v_mov_b64_e32 v[44:45], v[0:1]
	v_lshlrev_b32_e32 v39, 16, v30
	v_and_b32_e32 v38, 0xffff0000, v30
	v_lshlrev_b32_e32 v37, 16, v31
	v_and_b32_e32 v36, 0xffff0000, v31
	v_lshlrev_b32_e32 v31, 16, v46
	v_and_b32_e32 v30, 0xffff0000, v46
	v_and_b32_e32 v46, 0xffff0000, v22
	v_fmac_f32_e32 v16, v47, v47
	v_lshlrev_b32_e32 v33, 16, v45
	v_and_b32_e32 v32, 0xffff0000, v45
	v_lshlrev_b32_e32 v45, 16, v23
	v_fmac_f32_e32 v16, v46, v46
	v_lshlrev_b32_e32 v35, 16, v44
	v_and_b32_e32 v34, 0xffff0000, v44
	v_and_b32_e32 v44, 0xffff0000, v23
	v_fmac_f32_e32 v16, v45, v45
	v_fmac_f32_e32 v16, v44, v44
	ds_swizzle_b32 v17, v16 offset:swizzle(SWAP,1)
	s_add_i32 s1, s1, s2
	s_min_i32 s28, s1, 0x7fff
	s_ashr_i32 s29, s28, 31
	s_lshl_b64 s[28:29], s[28:29], 11
	s_waitcnt lgkmcnt(0)
	v_add_f32_e32 v16, v16, v17
	ds_swizzle_b32 v17, v16 offset:swizzle(SWAP,2)
	s_add_u32 s30, s4, s28
	s_addc_u32 s31, s5, s29
	s_add_u32 s28, s7, s28
	s_addc_u32 s29, s8, s29
	s_waitcnt lgkmcnt(0)
	v_add_f32_e32 v16, v16, v17
	ds_swizzle_b32 v17, v16 offset:swizzle(SWAP,4)
	v_lshl_add_u64 v[4:5], s[28:29], 0, v[24:25]
	v_lshl_add_u64 v[0:1], s[30:31], 0, v[24:25]
	global_load_dwordx4 v[8:11], v[0:1], off
	s_nop 0
	global_load_dwordx4 v[0:3], v[0:1], off offset:1024
	s_nop 0
	global_load_dwordx4 v[12:15], v[4:5], off
	s_nop 0
	global_load_dwordx4 v[4:7], v[4:5], off offset:1024
	s_waitcnt lgkmcnt(0)
	v_add_f32_e32 v16, v16, v17
	ds_swizzle_b32 v17, v16 offset:swizzle(SWAP,8)
	s_waitcnt lgkmcnt(0)
	v_add_f32_e32 v16, v16, v17
	ds_swizzle_b32 v17, v16 offset:swizzle(SWAP,16)
	s_waitcnt lgkmcnt(0)
	v_add_f32_e32 v16, v16, v17
	v_mov_b32_e32 v17, v16
	s_nop 1
	v_permlane32_swap_b32_e32 v16, v17
	v_add_f32_e32 v16, v16, v17
	v_fmamk_f32 v16, v16, 0x3a800000, v204
	v_cmp_gt_f32_e32 vcc, s81, v16
	v_mul_f32_e32 v17, 0x4f800000, v16
	s_nop 0
	v_cndmask_b32_e32 v16, v16, v17, vcc
	v_sqrt_f32_e32 v17, v16
	s_nop 0
	v_add_u32_e32 v18, -1, v17
	v_fma_f32 v19, -v18, v17, v16
	v_cmp_ge_f32_e64 s[42:43], 0, v19
	v_add_u32_e32 v19, 1, v17
	s_nop 0
	v_cndmask_b32_e64 v18, v17, v18, s[42:43]
	v_fma_f32 v17, -v19, v17, v16
	v_cmp_lt_f32_e64 s[42:43], 0, v17
	s_nop 1
	v_cndmask_b32_e64 v17, v18, v19, s[42:43]
	v_mul_f32_e32 v18, 0x37800000, v17
	v_cndmask_b32_e32 v17, v17, v18, vcc
	v_cmp_class_f32_e32 vcc, v16, v205
	s_nop 1
	v_cndmask_b32_e32 v16, v17, v16, vcc
	v_div_scale_f32 v17, s[28:29], v16, v16, 1.0
	v_rcp_f32_e32 v18, v17
	s_nop 0
	v_fma_f32 v19, -v17, v18, 1.0
	v_fmac_f32_e32 v18, v19, v18
	v_div_scale_f32 v19, vcc, 1.0, v16, 1.0
	v_mul_f32_e32 v20, v19, v18
	v_fma_f32 v21, -v17, v20, v19
	v_fmac_f32_e32 v20, v21, v18
	v_fma_f32 v17, -v17, v20, v19
	v_div_fmas_f32 v17, v17, v18, v20
	v_div_fixup_f32 v52, v17, v16, 1.0
	v_mul_f32_e32 v53, v52, v53
	v_mul_f32_e32 v51, v52, v51
	v_fmac_f32_e32 v41, v68, v53
	v_mul_f32_e32 v20, v52, v54
	v_fmac_f32_e32 v43, v69, v20
	v_mul_f32_e32 v20, v52, v55
	v_fmac_f32_e32 v42, v70, v20
	v_mul_f32_e32 v20, v52, v56
	v_fmac_f32_e32 v40, v71, v20
	v_mul_f32_e32 v20, v52, v57
	v_fmac_f32_e32 v39, v72, v20
	v_mul_f32_e32 v16, v52, v58
	v_fmac_f32_e32 v38, v73, v16
	v_mul_f32_e32 v16, v52, v59
	v_fmac_f32_e32 v37, v74, v16
	v_mul_f32_e32 v16, v52, v60
	v_fmac_f32_e32 v36, v75, v16
	v_fmac_f32_e32 v35, v76, v51
	v_mul_f32_e32 v20, v52, v50
	v_fmac_f32_e32 v34, v77, v20
	v_mul_f32_e32 v20, v52, v49
	v_fmac_f32_e32 v33, v78, v20
	v_mul_f32_e32 v22, v43, v43
	v_fmac_f32_e32 v22, v41, v41
	v_fmac_f32_e32 v22, v42, v42
	v_fmac_f32_e32 v22, v40, v40
	v_fmac_f32_e32 v22, v39, v39
	v_fmac_f32_e32 v22, v38, v38
	v_fmac_f32_e32 v22, v37, v37
	v_fmac_f32_e32 v22, v36, v36
	v_fmac_f32_e32 v22, v35, v35
	v_mul_f32_e32 v20, v52, v48
	v_fmac_f32_e32 v22, v34, v34
	v_fmac_f32_e32 v32, v79, v20
	v_mul_f32_e32 v20, v52, v47
	v_fmac_f32_e32 v22, v33, v33
	v_fmac_f32_e32 v31, v80, v20
	v_mul_f32_e32 v16, v52, v46
	v_fmac_f32_e32 v22, v32, v32
	v_fmac_f32_e32 v30, v81, v16
	v_mul_f32_e32 v16, v52, v45
	v_fmac_f32_e32 v22, v31, v31
	v_fmac_f32_e32 v29, v82, v16
	v_mul_f32_e32 v16, v52, v44
	v_fmac_f32_e32 v22, v30, v30
	v_fmac_f32_e32 v28, v83, v16
	v_cvt_pk_bf16_f32 v16, v41, v43
	v_lshl_add_u64 v[20:21], s[16:17], 0, v[24:25]
	v_fmac_f32_e32 v22, v29, v29
	v_cvt_pk_bf16_f32 v17, v42, v40
	v_cvt_pk_bf16_f32 v18, v39, v38
	v_cvt_pk_bf16_f32 v19, v37, v36
	global_store_dwordx4 v[20:21], v[16:19], off
	v_fmac_f32_e32 v22, v28, v28
	s_nop 0
	v_cvt_pk_bf16_f32 v16, v35, v34
	v_cvt_pk_bf16_f32 v17, v33, v32
	v_cvt_pk_bf16_f32 v18, v31, v30
	v_cvt_pk_bf16_f32 v19, v29, v28
	global_store_dwordx4 v[20:21], v[16:19], off offset:1024
	ds_swizzle_b32 v16, v22 offset:swizzle(SWAP,1)
	s_waitcnt lgkmcnt(0)
	v_add_f32_e32 v16, v22, v16
	ds_swizzle_b32 v17, v16 offset:swizzle(SWAP,2)
	s_waitcnt lgkmcnt(0)
	v_add_f32_e32 v16, v16, v17
	ds_swizzle_b32 v17, v16 offset:swizzle(SWAP,4)
	s_waitcnt lgkmcnt(0)
	v_add_f32_e32 v16, v16, v17
	ds_swizzle_b32 v17, v16 offset:swizzle(SWAP,8)
	s_waitcnt lgkmcnt(0)
	v_add_f32_e32 v16, v16, v17
	ds_swizzle_b32 v17, v16 offset:swizzle(SWAP,16)
	s_waitcnt lgkmcnt(0)
	v_add_f32_e32 v16, v16, v17
	v_mov_b32_e32 v17, v16
	s_nop 1
	v_permlane32_swap_b32_e32 v16, v17
	s_and_saveexec_b64 s[28:29], s[40:41]
	s_cbranch_execz .LBB0_198
; __device__ __forceinline__ unsigned cvt_pk_bf16(float lo, float hi) { unsigned r; asm volatile("v_cvt_pk_bf16_f32 %0, %1, %2" : "=v"(r) : "v"(lo), "v"(hi)); return r; }
; #define GASF __attribute__((address_space(1)))
; __device__ __forceinline__ void resid_rows(const float* xf_, bf16_t* XB_, const bf16_t* Y_, const float* gain_, float* R_, float* outf_, int rows, int gw, int NGW, int lane) {
;     ...
;         else { GASF u32x4* p = (GASF u32x4*)(XB_ + (size_t)row * DM); float ss = 0.f;
; #pragma unroll
;             for (int i = 0; i < 16; ++i) ss += v[i] * v[i];
; #pragma unroll
;             for (int j = 0; j < 2; ++j) { u32x4 w; w.x = cvt_pk_bf16(v[8 * j + 0], v[8 * j + 1]); w.y = cvt_pk_bf16(v[8 * j + 2], v[8 * j + 3]); w.z = cvt_pk_bf16(v[8 * j + 4], v[8 * j + 5]); w.w = cvt_pk_bf16(v[8 * j + 6], v[8 * j + 7]); p[lane + 64 * j] = w; }
;             ss = wave_sum(ss);
;             if (lane == 0) ((GASF float*)R_)[row] = 1.0f / sqrtf(ss * (1.f / DM) + EPS); }
	v_add_f32_e32 v16, v16, v17
	v_fmamk_f32 v16, v16, 0x3a800000, v204
	v_mul_f32_e32 v17, 0x4f800000, v16
	v_cmp_gt_f32_e32 vcc, s81, v16
	s_nop 1
	v_cndmask_b32_e32 v16, v16, v17, vcc
	v_sqrt_f32_e32 v17, v16
	s_nop 0
	v_add_u32_e32 v18, -1, v17
	v_fma_f32 v20, -v18, v17, v16
	v_add_u32_e32 v19, 1, v17
	v_cmp_ge_f32_e64 s[42:43], 0, v20
	s_nop 1
	v_cndmask_b32_e64 v18, v17, v18, s[42:43]
	v_fma_f32 v17, -v19, v17, v16
	v_cmp_lt_f32_e64 s[42:43], 0, v17
	s_nop 1
	v_cndmask_b32_e64 v17, v18, v19, s[42:43]
	v_mul_f32_e32 v18, 0x37800000, v17
	v_cndmask_b32_e32 v17, v17, v18, vcc
	v_cmp_class_f32_e32 vcc, v16, v205
	s_nop 1
	v_cndmask_b32_e32 v16, v17, v16, vcc
	v_div_scale_f32 v17, s[30:31], v16, v16, 1.0
	v_rcp_f32_e32 v18, v17
	s_nop 0
	v_fma_f32 v19, -v17, v18, 1.0
	v_fmac_f32_e32 v18, v19, v18
	v_div_scale_f32 v19, vcc, 1.0, v16, 1.0
	v_mul_f32_e32 v20, v19, v18
	v_fma_f32 v21, -v17, v20, v19
	v_fmac_f32_e32 v20, v21, v18
	v_fma_f32 v17, -v17, v20, v19
	v_div_fmas_f32 v17, v17, v18, v20
	v_div_fixup_f32 v16, v17, v16, 1.0
	global_store_dword v175, v16, s[18:19]
	s_branch .LBB0_198

; template <int ldq, int ldk, int ldv, int ldo>
; __device__ __forceinline__ void attn_mla_body2(const bf16_t* Qb_, const bf16_t* Kh_, const bf16_t* Vh_, bf16_t* Ob_, int seq, char* lds, const float* cs_, const float* sn_, int pos0, int tid_in) {
;     ...
;   f32x16 C0, C1; bf16x8 pa0, pa1, pa2, pa3; s16x4 a0, a1, a2, a3;
.LBB0_805:
	s_lshl_b32 s22, s22, 6
	s_ashr_i32 s23, s22, 31
	s_lshl_b64 s[46:47], s[22:23], 10
	v_lshl_add_u64 v[64:65], v[202:203], 0, s[46:47]
	s_mul_hi_i32 s47, s22, 0x600
	s_mul_i32 s46, s22, 0x600
	v_lshl_add_u64 v[66:67], v[200:201], 0, s[46:47]
	global_load_dwordx4 v[154:157], v[64:65], off
	global_load_dwordx4 v[158:161], v[66:67], off
	v_lshl_add_u64 v[64:65], v[198:199], 0, s[46:47]
	global_load_dwordx4 v[162:165], v[64:65], off
	s_waitcnt lgkmcnt(0)
	s_barrier
	s_setprio 3
	v_mfma_f32_32x32x16_bf16 v[0:15], v[106:109], v[170:173], v[0:15]
	s_waitcnt vmcnt(6)
	v_add_u32_e32 v92, s44, v214
	ds_read_b64_tr_b16 v[80:81], v92 offset:0x1000
	ds_read_b64_tr_b16 v[82:83], v92 offset:0x1800
	ds_read_b64_tr_b16 v[84:85], v92 offset:0x1200
	ds_read_b64_tr_b16 v[86:87], v92 offset:0x1a00
	ds_read_b64_tr_b16 v[182:183], v92 offset:0x2000
	ds_read_b64_tr_b16 v[184:185], v92 offset:0x2800
	ds_read_b64_tr_b16 v[250:251], v92 offset:0x2200
	ds_read_b64_tr_b16 v[252:253], v92 offset:0x2a00
	v_mfma_f32_32x32x16_bf16 v[16:31], v[106:109], v[166:169], v[16:31]
	v_mfma_f32_32x32x16_bf16 v[32:47], v[106:109], v[114:117], v[32:47]
	ds_read_b64_tr_b16 v[106:107], v92 offset:0x3000
	ds_read_b64_tr_b16 v[108:109], v92 offset:0x3800
	ds_read_b64_tr_b16 v[166:167], v92 offset:0x3200
	ds_read_b64_tr_b16 v[168:169], v92 offset:0x3a00
	v_mfma_f32_32x32x16_bf16 v[32:47], v[102:105], v[114:117], v[32:47]
	s_add_i32 s22, s43, 0
	v_add_u32_e32 v93, s22, v215
	ds_read_b128 v[88:91], v93 offset:49152
	ds_read_b128 v[224:227], v93 offset:57344
	v_add_u32_e32 v93, s22, v216
	ds_read_b128 v[228:231], v93 offset:49152
	ds_read_b128 v[232:235], v93 offset:57344
	s_waitcnt lgkmcnt(12)
	v_mfma_f32_32x32x16_bf16 v[0:15], v[102:105], v[80:83], v[0:15]
	v_mfma_f32_32x32x16_bf16 v[16:31], v[102:105], v[84:87], v[16:31]
	v_mfma_f32_32x32x16_bf16 v[32:47], v[98:101], v[114:117], v[32:47]
	v_add_u32_e32 v92, s22, v217
	ds_read_b128 v[170:173], v92 offset:49152
	ds_read_b128 v[236:239], v92 offset:57344
	v_add_u32_e32 v92, s22, v218
	ds_read_b128 v[240:243], v92 offset:49152
	ds_read_b128 v[244:247], v92 offset:57344
	s_waitcnt lgkmcnt(12)
	v_mfma_f32_32x32x16_bf16 v[0:15], v[98:101], v[182:185], v[0:15]
	v_mfma_f32_32x32x16_bf16 v[16:31], v[98:101], v[250:253], v[16:31]
	v_mfma_f32_32x32x16_bf16 v[32:47], v[94:97], v[114:117], v[32:47]
	s_waitcnt lgkmcnt(8)
	v_mfma_f32_32x32x16_bf16 v[0:15], v[94:97], v[106:109], v[0:15]
	v_mfma_f32_32x32x16_bf16 v[16:31], v[94:97], v[166:169], v[16:31]
	v_add_u32_e32 v92, s22, v219
	ds_read_b128 v[182:185], v92 offset:49152
	ds_read_b128 v[250:253], v92 offset:57344
	s_waitcnt lgkmcnt(6)
	v_mfma_f32_32x32x16_bf16 v[96:111], v[88:91], v[118:121], v[48:63]
	v_add_u32_e32 v176, s22, v220
	v_mfma_f32_32x32x16_bf16 v[80:95], v[224:227], v[118:121], v[48:63]
	v_mfma_f32_32x32x16_bf16 v[96:111], v[228:231], v[122:125], v[96:111]
	v_mfma_f32_32x32x16_bf16 v[80:95], v[232:235], v[122:125], v[80:95]
	ds_read_b128 v[224:227], v176 offset:49152
	ds_read_b128 v[228:231], v176 offset:57344
	s_waitcnt lgkmcnt(7)
	v_mfma_f32_32x32x16_bf16 v[96:111], v[170:173], v[126:129], v[96:111]
	s_waitcnt lgkmcnt(6)
	v_mfma_f32_32x32x16_bf16 v[80:95], v[236:239], v[126:129], v[80:95]
	s_waitcnt lgkmcnt(5)
	v_mfma_f32_32x32x16_bf16 v[96:111], v[240:243], v[130:133], v[96:111]
	s_waitcnt lgkmcnt(4)
	v_mfma_f32_32x32x16_bf16 v[80:95], v[244:247], v[130:133], v[80:95]
	s_waitcnt lgkmcnt(3)
	v_mfma_f32_32x32x16_bf16 v[96:111], v[182:185], v[134:137], v[96:111]
	s_waitcnt lgkmcnt(2)
	v_mfma_f32_32x32x16_bf16 v[80:95], v[250:253], v[134:137], v[80:95]
	s_waitcnt lgkmcnt(1)
	v_mfma_f32_32x32x16_bf16 v[96:111], v[224:227], v[138:141], v[96:111]
	s_waitcnt lgkmcnt(0)
	v_mfma_f32_32x32x16_bf16 v[80:95], v[228:231], v[138:141], v[80:95]
	s_setprio 0
	s_nop 8
	v_max3_f32 v166, v96, v97, v98
	v_max3_f32 v167, v99, v100, v101
	v_max3_f32 v166, v166, v102, v103
	v_max3_f32 v167, v167, v104, v105
	v_max3_f32 v166, v166, v106, v107
	v_max3_f32 v167, v167, v108, v109
	v_max3_f32 v166, v166, v110, v111
	v_max3_f32 v167, v167, v80, v81
	v_max3_f32 v166, v166, v82, v83
	v_max3_f32 v167, v167, v84, v85
	v_max3_f32 v166, v166, v86, v87
	v_max3_f32 v167, v167, v88, v89
	v_max3_f32 v166, v166, v90, v91
	v_max3_f32 v167, v167, v92, v93
	v_max3_f32 v166, v166, v94, v95
	v_max_f32_e32 v166, v166, v167
	v_mov_b32_e32 v167, v166
	s_nop 1
	v_permlane32_swap_b32_e32 v166, v167
	v_max_f32_e32 v166, v166, v167
	v_cmp_lt_f32_e32 vcc, s97, v166
	s_barrier
	s_cbranch_vccnz .LBB0_814

; template <int ldq, int ldk, int ldv, int ldo>
; __device__ __forceinline__ void attn_mla_body2(const bf16_t* Qb_, const bf16_t* Kh_, const bf16_t* Vh_, bf16_t* Ob_, int seq, char* lds, const float* cs_, const float* sn_, int pos0, int tid_in) {
;     ...
;   f32x16 C0, C1; bf16x8 pa0, pa1, pa2, pa3; s16x4 a0, a1, a2, a3;
.LBB0_809:
	s_add_i32 s22, s45, -1
	s_min_i32 s44, s22, s69
	s_lshl_b32 s22, s44, 6
	s_ashr_i32 s23, s22, 31
	s_mul_i32 s44, s44, 0x18000
	s_mul_hi_i32 s47, s22, 0x600
	s_add_u32 s46, s18, s44
	s_addc_u32 s47, s19, s47
	s_lshl_b64 s[22:23], s[22:23], 10
	v_lshl_add_u64 v[106:107], v[194:195], 1, s[46:47]
	v_lshl_add_u64 v[108:109], v[196:197], 1, s[46:47]
	global_load_dwordx4 v[142:145], v[106:107], off
	global_load_dwordx4 v[146:149], v[108:109], off
	v_lshl_add_u64 v[106:107], v[202:203], 0, s[22:23]
	global_load_dwordx4 v[150:153], v[106:107], off
	s_add_i32 s22, s43, 0x4000
	s_cmpk_lg_u32 s43, 0x8000
	s_cselect_b32 s44, s22, 0
	s_waitcnt lgkmcnt(0)
	s_barrier
	s_setprio 3
	v_mfma_f32_32x32x16_bf16 v[0:15], v[92:95], v[100:103], v[0:15]
	ds_read_b64_tr_b16 v[106:107], v104 offset:0x1000
	ds_read_b64_tr_b16 v[108:109], v104 offset:0x1800
	ds_read_b64_tr_b16 v[166:167], v104 offset:0x1200
	ds_read_b64_tr_b16 v[168:169], v104 offset:0x1a00
	ds_read_b64_tr_b16 v[182:183], v104 offset:0x2000
	ds_read_b64_tr_b16 v[184:185], v104 offset:0x2800
	ds_read_b64_tr_b16 v[250:251], v104 offset:0x2200
	ds_read_b64_tr_b16 v[252:253], v104 offset:0x2a00
	v_mfma_f32_32x32x16_bf16 v[16:31], v[92:95], v[96:99], v[16:31]
	v_mfma_f32_32x32x16_bf16 v[32:47], v[92:95], v[114:117], v[32:47]
	ds_read_b64_tr_b16 v[100:101], v104 offset:0x3000
	ds_read_b64_tr_b16 v[102:103], v104 offset:0x3800
	ds_read_b64_tr_b16 v[96:97], v104 offset:0x3200
	ds_read_b64_tr_b16 v[98:99], v104 offset:0x3a00
	v_mfma_f32_32x32x16_bf16 v[32:47], v[88:91], v[114:117], v[32:47]
	s_add_i32 s22, s44, 0
	v_add_u32_e32 v105, s22, v215
	ds_read_b128 v[170:173], v105 offset:49152
	ds_read_b128 v[224:227], v105 offset:57344
	v_add_u32_e32 v105, s22, v216
	ds_read_b128 v[228:231], v105 offset:49152
	ds_read_b128 v[232:235], v105 offset:57344
	s_waitcnt lgkmcnt(12)
	v_mfma_f32_32x32x16_bf16 v[0:15], v[88:91], v[106:109], v[0:15]
	v_mfma_f32_32x32x16_bf16 v[16:31], v[88:91], v[166:169], v[16:31]
	v_mfma_f32_32x32x16_bf16 v[32:47], v[84:87], v[114:117], v[32:47]
	v_add_u32_e32 v105, s22, v217
	ds_read_b128 v[166:169], v105 offset:49152
	ds_read_b128 v[236:239], v105 offset:57344
	v_add_u32_e32 v105, s22, v218
	ds_read_b128 v[240:243], v105 offset:49152
	ds_read_b128 v[244:247], v105 offset:57344
	s_waitcnt lgkmcnt(12)
	v_mfma_f32_32x32x16_bf16 v[0:15], v[84:87], v[182:185], v[0:15]
	v_mfma_f32_32x32x16_bf16 v[16:31], v[84:87], v[250:253], v[16:31]
	v_mfma_f32_32x32x16_bf16 v[32:47], v[80:83], v[114:117], v[32:47]
	s_waitcnt lgkmcnt(8)
	v_mfma_f32_32x32x16_bf16 v[0:15], v[80:83], v[100:103], v[0:15]
	v_mfma_f32_32x32x16_bf16 v[16:31], v[80:83], v[96:99], v[16:31]
	v_add_u32_e32 v105, s22, v219
	ds_read_b128 v[182:185], v105 offset:49152
	ds_read_b128 v[250:253], v105 offset:57344
	s_waitcnt lgkmcnt(6)
	v_mfma_f32_32x32x16_bf16 v[80:95], v[170:173], v[118:121], v[48:63]
	v_add_u32_e32 v104, s22, v220
	v_mfma_f32_32x32x16_bf16 v[64:79], v[224:227], v[118:121], v[48:63]
	v_mfma_f32_32x32x16_bf16 v[80:95], v[228:231], v[122:125], v[80:95]
	v_mfma_f32_32x32x16_bf16 v[64:79], v[232:235], v[122:125], v[64:79]
	ds_read_b128 v[224:227], v104 offset:49152
	ds_read_b128 v[228:231], v104 offset:57344
	s_waitcnt lgkmcnt(7)
	v_mfma_f32_32x32x16_bf16 v[80:95], v[166:169], v[126:129], v[80:95]
	s_waitcnt lgkmcnt(6)
	v_mfma_f32_32x32x16_bf16 v[64:79], v[236:239], v[126:129], v[64:79]
	s_waitcnt lgkmcnt(5)
	v_mfma_f32_32x32x16_bf16 v[80:95], v[240:243], v[130:133], v[80:95]
	s_waitcnt lgkmcnt(4)
	v_mfma_f32_32x32x16_bf16 v[64:79], v[244:247], v[130:133], v[64:79]
	s_waitcnt lgkmcnt(3)
	v_mfma_f32_32x32x16_bf16 v[80:95], v[182:185], v[134:137], v[80:95]
	s_waitcnt lgkmcnt(2)
	v_mfma_f32_32x32x16_bf16 v[64:79], v[250:253], v[134:137], v[64:79]
	s_waitcnt lgkmcnt(1)
	v_mfma_f32_32x32x16_bf16 v[80:95], v[224:227], v[138:141], v[80:95]
	s_waitcnt lgkmcnt(0)
	v_mfma_f32_32x32x16_bf16 v[64:79], v[228:231], v[138:141], v[64:79]
	s_setprio 0
	s_nop 8
	v_max3_f32 v96, v80, v81, v82
	v_max3_f32 v97, v83, v84, v85
	v_max3_f32 v96, v96, v86, v87
	v_max3_f32 v97, v97, v88, v89
	v_max3_f32 v96, v96, v90, v91
	v_max3_f32 v97, v97, v92, v93
	v_max3_f32 v96, v96, v94, v95
	v_max3_f32 v97, v97, v64, v65
	v_max3_f32 v96, v96, v66, v67
	v_max3_f32 v97, v97, v68, v69
	v_max3_f32 v96, v96, v70, v71
	v_max3_f32 v97, v97, v72, v73
	v_max3_f32 v96, v96, v74, v75
	v_max3_f32 v97, v97, v76, v77
	v_max3_f32 v96, v96, v78, v79
	v_max_f32_e32 v96, v96, v97
	v_mov_b32_e32 v97, v96
	s_nop 1
	v_permlane32_swap_b32_e32 v96, v97
	v_max_f32_e32 v96, v96, v97
	v_cmp_lt_f32_e32 vcc, s97, v96
	s_barrier
	s_cbranch_vccnz .LBB0_817

; #define GASF __attribute__((address_space(1)))
; __device__ __forceinline__ void resid_rows(const float* xf_, bf16_t* XB_, const bf16_t* Y_, const float* gain_, float* R_, float* outf_, int rows, int gw, int NGW, int lane) {
;     u32x4 xw[2], yw[2], nxw[2], nyw[2]; f32x4 xv[4], nxv[4];
;     const int last = rows - 1;
;     ...
;     RR_LOAD(xw, yw, xv, gw);
;     for (int row = gw; row < rows; row += NGW) {
;     ...
;             const GASF f32x4* gp = (const GASF f32x4*)gain_;
; #pragma unroll
;             for (int j = 0; j < 2; ++j) { const f32x4 a = gp[lane * 2 + 128 * j], b = gp[lane * 2 + 1 + 128 * j];
.LBB0_1267:
	s_load_dwordx2 s[16:17], s[12:13], 0xc8
	s_lshl_b32 s2, s1, 3
	v_mbcnt_lo_u32_b32 v0, -1, v0
	v_mbcnt_hi_u32_b32 v16, -1, v0
	v_ashrrev_i32_e32 v17, 31, v16
	s_waitcnt lgkmcnt(0)
	s_add_u32 s4, s16, 0x19800000
	s_addc_u32 s7, s17, 0
	s_add_u32 s8, s16, 0x2c800000
	s_addc_u32 s22, s17, 0
	s_ashr_i32 s1, s0, 31
	s_lshl_b64 s[18:19], s[0:1], 11
	s_add_u32 s20, s8, s18
	s_addc_u32 s21, s22, s19
	s_add_u32 s18, s4, s18
	v_lshlrev_b64 v[24:25], 4, v[16:17]
	s_addc_u32 s19, s7, s19
	v_lshl_add_u64 v[0:1], s[20:21], 0, v[24:25]
	v_lshl_add_u64 v[4:5], s[18:19], 0, v[24:25]
	s_load_dwordx2 s[12:13], s[12:13], 0x98
	global_load_dwordx4 v[8:11], v[0:1], off offset:1024
	global_load_dwordx4 v[12:15], v[0:1], off
	s_nop 0
	global_load_dwordx4 v[0:3], v[4:5], off offset:1024
	s_nop 0
	global_load_dwordx4 v[4:7], v[4:5], off
	v_readlane_b32 s1, v255, 41
	s_lshl_b32 s10, s1, 10
	s_lshl_b64 s[18:19], s[10:11], 2
	s_waitcnt lgkmcnt(0)
	s_add_u32 s12, s12, s18
	s_addc_u32 s13, s13, s19
	s_ashr_i32 s1, s3, 31
	s_ashr_i32 s10, s14, 31
	v_lshlrev_b32_e32 v18, 1, v16
	s_add_u32 s18, s3, s14
	v_ashrrev_i32_e32 v19, 31, v18
	s_addc_u32 s19, s1, s10
	v_lshl_add_u64 v[26:27], v[18:19], 4, s[12:13]
	s_lshl_b64 s[12:13], s[18:19], 2
	s_add_u32 s1, s16, s12
	s_addc_u32 s3, s17, s13
	s_add_u32 s12, s1, 0x30840000
	s_addc_u32 s13, s3, 0
	s_ashr_i32 s3, s2, 31
	s_lshl_b64 s[14:15], s[2:3], 2
	s_lshl_b64 s[16:17], s[18:19], 11
	s_add_u32 s16, s4, s16
	v_cmp_eq_u32_e64 s[40:41], 0, v16
	s_addc_u32 s17, s7, s17
	s_lshl_b64 s[18:19], s[2:3], 11
	global_load_dwordx4 v[68:71], v[26:27], off
	global_load_dwordx4 v[72:75], v[26:27], off offset:16
	global_load_dwordx4 v[76:79], v[26:27], off offset:2048
	global_load_dwordx4 v[80:83], v[26:27], off offset:2064
	s_waitcnt vmcnt(0)
	s_branch .LBB0_1269

; __device__ __forceinline__ void resid_rows(const float* xf_, bf16_t* XB_, const bf16_t* Y_, const float* gain_, float* R_, float* outf_, int rows, int gw, int NGW, int lane) {
;     ...
;     for (int row = gw; row < rows; row += NGW) {
;         RR_LOAD(nxw, nyw, nxv, row + NGW);
;         float v[16];
;         if (xf_) {
; #pragma unroll
;             for (int j = 0; j < 2; ++j) { const f32x4 a = xv[2 * j], b = xv[2 * j + 1];
;                 v[8 * j + 0] = a.x; v[8 * j + 1] = a.y; v[8 * j + 2] = a.z; v[8 * j + 3] = a.w; v[8 * j + 4] = b.x; v[8 * j + 5] = b.y; v[8 * j + 6] = b.z; v[8 * j + 7] = b.w; } }
;         else {
; #pragma unroll
;             for (int j = 0; j < 2; ++j) { const u32x4 w = xw[j];
;                 v[8 * j + 0] = bf_lo(w.x); v[8 * j + 1] = bf_hi(w.x); v[8 * j + 2] = bf_lo(w.y); v[8 * j + 3] = bf_hi(w.y); v[8 * j + 4] = bf_lo(w.z); v[8 * j + 5] = bf_hi(w.z); v[8 * j + 6] = bf_lo(w.w); v[8 * j + 7] = bf_hi(w.w); } }
;         if (Y_) { float y[16]; float ss = 0.f;
; #pragma unroll
;             for (int j = 0; j < 2; ++j) { const u32x4 w = yw[j];
;                 y[8 * j + 0] = bf_lo(w.x); y[8 * j + 1] = bf_hi(w.x); y[8 * j + 2] = bf_lo(w.y); y[8 * j + 3] = bf_hi(w.y); y[8 * j + 4] = bf_lo(w.z); y[8 * j + 5] = bf_hi(w.z); y[8 * j + 6] = bf_lo(w.w); y[8 * j + 7] = bf_hi(w.w); }
; #pragma unroll
;             for (int i = 0; i < 16; ++i) ss += y[i] * y[i];
;             const float r = 1.0f / sqrtf(wave_sum(ss) * (1.f / DM) + EPS);
;             const GASF f32x4* gp = (const GASF f32x4*)gain_;
; #pragma unroll
;             for (int j = 0; j < 2; ++j) { const f32x4 a = gp[lane * 2 + 128 * j], b = gp[lane * 2 + 1 + 128 * j];
;                 v[8 * j + 0] += y[8 * j + 0] * r * a.x; v[8 * j + 1] += y[8 * j + 1] * r * a.y; v[8 * j + 2] += y[8 * j + 2] * r * a.z; v[8 * j + 3] += y[8 * j + 3] * r * a.w;
;                 v[8 * j + 4] += y[8 * j + 4] * r * b.x; v[8 * j + 5] += y[8 * j + 5] * r * b.y; v[8 * j + 6] += y[8 * j + 6] * r * b.z; v[8 * j + 7] += y[8 * j + 7] * r * b.w; } }
;         if (outf_) { GASF f32x4* p = (GASF f32x4*)(outf_ + (size_t)row * DM);
; #pragma unroll
;             for (int j = 0; j < 2; ++j) { p[lane * 2 + 128 * j] = (f32x4){v[8 * j + 0], v[8 * j + 1], v[8 * j + 2], v[8 * j + 3]}; p[lane * 2 + 1 + 128 * j] = (f32x4){v[8 * j + 4], v[8 * j + 5], v[8 * j + 6], v[8 * j + 7]}; } }
.LBB0_1269:
	s_waitcnt vmcnt(3)
	v_mov_b64_e32 v[18:19], v[14:15]
	v_mov_b64_e32 v[16:17], v[12:13]
	v_and_b32_e32 v54, 0xffff0000, v16
	v_lshlrev_b32_e32 v53, 16, v16
	v_mul_f32_e32 v16, v54, v54
	v_lshlrev_b32_e32 v55, 16, v17
	v_fmac_f32_e32 v16, v53, v53
	v_and_b32_e32 v56, 0xffff0000, v17
	v_fmac_f32_e32 v16, v55, v55
	v_lshlrev_b32_e32 v57, 16, v18
	v_fmac_f32_e32 v16, v56, v56
	v_and_b32_e32 v58, 0xffff0000, v18
	v_fmac_f32_e32 v16, v57, v57
	v_mov_b64_e32 v[22:23], v[10:11]
	v_lshlrev_b32_e32 v59, 16, v19
	v_fmac_f32_e32 v16, v58, v58
	v_mov_b64_e32 v[20:21], v[8:9]
	v_and_b32_e32 v60, 0xffff0000, v19
	v_fmac_f32_e32 v16, v59, v59
	v_lshlrev_b32_e32 v51, 16, v20
	v_fmac_f32_e32 v16, v60, v60
	v_and_b32_e32 v50, 0xffff0000, v20
	v_fmac_f32_e32 v16, v51, v51
	s_nop 0
	v_mov_b64_e32 v[30:31], v[6:7]
	v_lshlrev_b32_e32 v49, 16, v21
	v_fmac_f32_e32 v16, v50, v50
	v_mov_b64_e32 v[28:29], v[4:5]
	v_mov_b64_e32 v[46:47], v[2:3]
	v_and_b32_e32 v48, 0xffff0000, v21
	v_fmac_f32_e32 v16, v49, v49
	v_lshlrev_b32_e32 v41, 16, v28
	v_and_b32_e32 v43, 0xffff0000, v28
	v_lshlrev_b32_e32 v42, 16, v29
	v_and_b32_e32 v40, 0xffff0000, v29
	v_lshlrev_b32_e32 v29, 16, v47
	v_and_b32_e32 v28, 0xffff0000, v47
	v_lshlrev_b32_e32 v47, 16, v22
	v_fmac_f32_e32 v16, v48, v48
	v_mov_b64_e32 v[44:45], v[0:1]
	v_lshlrev_b32_e32 v39, 16, v30
	v_and_b32_e32 v38, 0xffff0000, v30
	v_lshlrev_b32_e32 v37, 16, v31
	v_and_b32_e32 v36, 0xffff0000, v31
	v_lshlrev_b32_e32 v31, 16, v46
	v_and_b32_e32 v30, 0xffff0000, v46
	v_and_b32_e32 v46, 0xffff0000, v22
	v_fmac_f32_e32 v16, v47, v47
	v_lshlrev_b32_e32 v33, 16, v45
	v_and_b32_e32 v32, 0xffff0000, v45
	v_lshlrev_b32_e32 v45, 16, v23
	v_fmac_f32_e32 v16, v46, v46
	v_lshlrev_b32_e32 v35, 16, v44
	v_and_b32_e32 v34, 0xffff0000, v44
	v_and_b32_e32 v44, 0xffff0000, v23
	v_fmac_f32_e32 v16, v45, v45
	v_fmac_f32_e32 v16, v44, v44
	ds_swizzle_b32 v17, v16 offset:swizzle(SWAP,1)
	s_add_i32 s0, s0, s2
	s_min_i32 s20, s0, 0x7fff
	s_ashr_i32 s21, s20, 31
	s_lshl_b64 s[20:21], s[20:21], 11
	s_waitcnt lgkmcnt(0)
	v_add_f32_e32 v16, v16, v17
	ds_swizzle_b32 v17, v16 offset:swizzle(SWAP,2)
	s_add_u32 s28, s4, s20
	s_addc_u32 s29, s7, s21
	s_add_u32 s20, s8, s20
	s_addc_u32 s21, s22, s21
	s_waitcnt lgkmcnt(0)
	v_add_f32_e32 v16, v16, v17
	ds_swizzle_b32 v17, v16 offset:swizzle(SWAP,4)
	v_lshl_add_u64 v[8:9], s[20:21], 0, v[24:25]
	v_lshl_add_u64 v[0:1], s[28:29], 0, v[24:25]
	global_load_dwordx4 v[4:7], v[0:1], off
	s_nop 0
	global_load_dwordx4 v[0:3], v[0:1], off offset:1024
	s_nop 0
	global_load_dwordx4 v[12:15], v[8:9], off
	s_nop 0
	global_load_dwordx4 v[8:11], v[8:9], off offset:1024
	s_waitcnt lgkmcnt(0)
	v_add_f32_e32 v16, v16, v17
	ds_swizzle_b32 v17, v16 offset:swizzle(SWAP,8)
	s_waitcnt lgkmcnt(0)
	v_add_f32_e32 v16, v16, v17
	ds_swizzle_b32 v17, v16 offset:swizzle(SWAP,16)
	s_waitcnt lgkmcnt(0)
	v_add_f32_e32 v16, v16, v17
	v_mov_b32_e32 v17, v16
	s_nop 1
	v_permlane32_swap_b32_e32 v16, v17
	v_add_f32_e32 v16, v16, v17
	v_fmamk_f32 v16, v16, 0x3a800000, v204
	v_cmp_gt_f32_e32 vcc, s81, v16
	v_mul_f32_e32 v17, 0x4f800000, v16
	s_nop 0
	v_cndmask_b32_e32 v16, v16, v17, vcc
	v_sqrt_f32_e32 v17, v16
	s_nop 0
	v_add_u32_e32 v18, -1, v17
	v_fma_f32 v19, -v18, v17, v16
	v_cmp_ge_f32_e64 s[42:43], 0, v19
	v_add_u32_e32 v19, 1, v17
	s_nop 0
	v_cndmask_b32_e64 v18, v17, v18, s[42:43]
	v_fma_f32 v17, -v19, v17, v16
	v_cmp_lt_f32_e64 s[42:43], 0, v17
	s_nop 1
	v_cndmask_b32_e64 v17, v18, v19, s[42:43]
	v_mul_f32_e32 v18, 0x37800000, v17
	v_cndmask_b32_e32 v17, v17, v18, vcc
	v_cmp_class_f32_e32 vcc, v16, v205
	s_nop 1
	v_cndmask_b32_e32 v16, v17, v16, vcc
	v_div_scale_f32 v17, s[20:21], v16, v16, 1.0
	v_rcp_f32_e32 v18, v17
	s_nop 0
	v_fma_f32 v19, -v17, v18, 1.0
	v_fmac_f32_e32 v18, v19, v18
	v_div_scale_f32 v19, vcc, 1.0, v16, 1.0
	v_mul_f32_e32 v20, v19, v18
	v_fma_f32 v21, -v17, v20, v19
	v_fmac_f32_e32 v20, v21, v18
	v_fma_f32 v17, -v17, v20, v19
	v_div_fmas_f32 v17, v17, v18, v20
	v_div_fixup_f32 v52, v17, v16, 1.0
	v_mul_f32_e32 v53, v52, v53
	v_mul_f32_e32 v51, v52, v51
	v_fmac_f32_e32 v41, v68, v53
	v_mul_f32_e32 v20, v52, v54
	v_fmac_f32_e32 v43, v69, v20
	v_mul_f32_e32 v20, v52, v55
	v_fmac_f32_e32 v42, v70, v20
	v_mul_f32_e32 v20, v52, v56
	v_fmac_f32_e32 v40, v71, v20
	v_mul_f32_e32 v20, v52, v57
	v_fmac_f32_e32 v39, v72, v20
	v_mul_f32_e32 v16, v52, v58
	v_fmac_f32_e32 v38, v73, v16
	v_mul_f32_e32 v16, v52, v59
	v_fmac_f32_e32 v37, v74, v16
	v_mul_f32_e32 v16, v52, v60
	v_fmac_f32_e32 v36, v75, v16
	v_fmac_f32_e32 v35, v76, v51
	v_mul_f32_e32 v20, v52, v50
	v_fmac_f32_e32 v34, v77, v20
	v_mul_f32_e32 v20, v52, v49
	v_fmac_f32_e32 v33, v78, v20
	v_mul_f32_e32 v22, v43, v43
	v_fmac_f32_e32 v22, v41, v41
	v_fmac_f32_e32 v22, v42, v42
	v_fmac_f32_e32 v22, v40, v40
	v_fmac_f32_e32 v22, v39, v39
	v_fmac_f32_e32 v22, v38, v38
	v_fmac_f32_e32 v22, v37, v37
	v_fmac_f32_e32 v22, v36, v36
	v_fmac_f32_e32 v22, v35, v35
	v_mul_f32_e32 v20, v52, v48
	v_fmac_f32_e32 v22, v34, v34
	v_fmac_f32_e32 v32, v79, v20
	v_mul_f32_e32 v20, v52, v47
	v_fmac_f32_e32 v22, v33, v33
	v_fmac_f32_e32 v31, v80, v20
	v_mul_f32_e32 v16, v52, v46
	v_fmac_f32_e32 v22, v32, v32
	v_fmac_f32_e32 v30, v81, v16
	v_mul_f32_e32 v16, v52, v45
	v_fmac_f32_e32 v22, v31, v31
	v_fmac_f32_e32 v29, v82, v16
	v_mul_f32_e32 v16, v52, v44
	v_fmac_f32_e32 v22, v30, v30
	v_fmac_f32_e32 v28, v83, v16
	v_cvt_pk_bf16_f32 v16, v41, v43
	v_lshl_add_u64 v[20:21], s[16:17], 0, v[24:25]
	v_fmac_f32_e32 v22, v29, v29
	v_cvt_pk_bf16_f32 v17, v42, v40
	v_cvt_pk_bf16_f32 v18, v39, v38
	v_cvt_pk_bf16_f32 v19, v37, v36
	global_store_dwordx4 v[20:21], v[16:19], off
	v_fmac_f32_e32 v22, v28, v28
	s_nop 0
	v_cvt_pk_bf16_f32 v16, v35, v34
	v_cvt_pk_bf16_f32 v17, v33, v32
	v_cvt_pk_bf16_f32 v18, v31, v30
	v_cvt_pk_bf16_f32 v19, v29, v28
	global_store_dwordx4 v[20:21], v[16:19], off offset:1024
	ds_swizzle_b32 v16, v22 offset:swizzle(SWAP,1)
	s_waitcnt lgkmcnt(0)
	v_add_f32_e32 v16, v22, v16
	ds_swizzle_b32 v17, v16 offset:swizzle(SWAP,2)
	s_waitcnt lgkmcnt(0)
	v_add_f32_e32 v16, v16, v17
	ds_swizzle_b32 v17, v16 offset:swizzle(SWAP,4)
	s_waitcnt lgkmcnt(0)
	v_add_f32_e32 v16, v16, v17
	ds_swizzle_b32 v17, v16 offset:swizzle(SWAP,8)
	s_waitcnt lgkmcnt(0)
	v_add_f32_e32 v16, v16, v17
	ds_swizzle_b32 v17, v16 offset:swizzle(SWAP,16)
	s_waitcnt lgkmcnt(0)
	v_add_f32_e32 v16, v16, v17
	v_mov_b32_e32 v17, v16
	s_nop 1
	v_permlane32_swap_b32_e32 v16, v17
	s_and_saveexec_b64 s[20:21], s[40:41]
	s_cbranch_execz .LBB0_1268
; __device__ __forceinline__ unsigned cvt_pk_bf16(float lo, float hi) { unsigned r; asm volatile("v_cvt_pk_bf16_f32 %0, %1, %2" : "=v"(r) : "v"(lo), "v"(hi)); return r; }
; #define GASF __attribute__((address_space(1)))
; __device__ __forceinline__ void resid_rows(const float* xf_, bf16_t* XB_, const bf16_t* Y_, const float* gain_, float* R_, float* outf_, int rows, int gw, int NGW, int lane) {
;     ...
;         else { GASF u32x4* p = (GASF u32x4*)(XB_ + (size_t)row * DM); float ss = 0.f;
; #pragma unroll
;             for (int i = 0; i < 16; ++i) ss += v[i] * v[i];
; #pragma unroll
;             for (int j = 0; j < 2; ++j) { u32x4 w; w.x = cvt_pk_bf16(v[8 * j + 0], v[8 * j + 1]); w.y = cvt_pk_bf16(v[8 * j + 2], v[8 * j + 3]); w.z = cvt_pk_bf16(v[8 * j + 4], v[8 * j + 5]); w.w = cvt_pk_bf16(v[8 * j + 6], v[8 * j + 7]); p[lane + 64 * j] = w; }
;             ss = wave_sum(ss);
;             if (lane == 0) ((GASF float*)R_)[row] = 1.0f / sqrtf(ss * (1.f / DM) + EPS); }
	v_add_f32_e32 v16, v16, v17
	v_fmamk_f32 v16, v16, 0x3a800000, v204
	v_mul_f32_e32 v17, 0x4f800000, v16
	v_cmp_gt_f32_e32 vcc, s81, v16
	s_nop 1
	v_cndmask_b32_e32 v16, v16, v17, vcc
	v_sqrt_f32_e32 v17, v16
	s_nop 0
	v_add_u32_e32 v18, -1, v17
	v_fma_f32 v20, -v18, v17, v16
	v_add_u32_e32 v19, 1, v17
	v_cmp_ge_f32_e64 s[42:43], 0, v20
	s_nop 1
	v_cndmask_b32_e64 v18, v17, v18, s[42:43]
	v_fma_f32 v17, -v19, v17, v16
	v_cmp_lt_f32_e64 s[42:43], 0, v17
	s_nop 1
	v_cndmask_b32_e64 v17, v18, v19, s[42:43]
	v_mul_f32_e32 v18, 0x37800000, v17
	v_cndmask_b32_e32 v17, v17, v18, vcc
	v_cmp_class_f32_e32 vcc, v16, v205
	s_nop 1
	v_cndmask_b32_e32 v16, v17, v16, vcc
	v_div_scale_f32 v17, s[28:29], v16, v16, 1.0
	v_rcp_f32_e32 v18, v17
	s_nop 0
	v_fma_f32 v19, -v17, v18, 1.0
	v_fmac_f32_e32 v18, v19, v18
	v_div_scale_f32 v19, vcc, 1.0, v16, 1.0
	v_mul_f32_e32 v20, v19, v18
	v_fma_f32 v21, -v17, v20, v19
	v_fmac_f32_e32 v20, v21, v18
	v_fma_f32 v17, -v17, v20, v19
	v_div_fmas_f32 v17, v17, v18, v20
	v_div_fixup_f32 v16, v17, v16, 1.0
	global_store_dword v175, v16, s[12:13]
	s_branch .LBB0_1268
